# dn as 256x128 supertile (1 round) with batched residual epilogue
# baseline (speedup 1.0000x reference)
; #define TIDX opaque_tid()
; DI int opaque0() { int z = 0; asm volatile("" : "+v"(z)); return z; }
; template <int AI, int BI>
; DI void gemm_stage(const u16* __restrict__ A, int lda, const u16* __restrict__ B, int ldb, char* buf, int tid) {
; #pragma unroll
;   for (int i = 0; i < 2 * AI; ++i) {
;     const int S = tid + NTHR * i, row = S >> 3, c = (S & 7) ^ ((row >> 1) & 7);
;     __builtin_amdgcn_global_load_lds((const unsigned*)(A + (size_t)row * lda + c * 8), (__attribute__((address_space(3))) unsigned*)(buf + S * 16), 16, 0, 0);
;   }
; #pragma unroll
;   for (int i = 0; i < 2 * BI; ++i) {
;     const int S = tid + NTHR * i, row = S >> 3, c = (S & 7) ^ ((row >> 1) & 7);
;     __builtin_amdgcn_global_load_lds((const unsigned*)(B + (size_t)row * ldb + c * 8), (__attribute__((address_space(3))) unsigned*)(buf + 16384 + S * 16), 16, 0, 0);
;   }
; }
; template <int AI, int BI>
; DI void gemm_tile(const u16* __restrict__ A, int lda, const u16* __restrict__ B, int ldb, int nk, bool swap,
;                   f32x16 (&acc)[AI][BI], char* lds) {
;   const int tid = TIDX, lane = tid & 63, wid = tid >> 6;
;   gemm_stage<AI, BI>(A, lda, B, ldb, lds, tid);
;   asm volatile("s_waitcnt vmcnt(0)" ::: "memory");
;   __syncthreads();
; template <int AI, int BI>
; DI void dn_tile(const Params& p, char* wsb, int layer, int sub, bool final_out, int m0, int n0, char* lds) {
;   const u16* HID = (const u16*)(wsb + OFF_HID);
;   const u16* W = (const u16*)(wsb + OFF_W) + (sub ? W_D1 : W_D0);
;   float* xs = (float*)(wsb + OFF_XS);
;   const float* mods = (const float*)(wsb + OFF_MODS) + (size_t)layer * 9 * 9216;
;   const int lane = TIDX & 63, wid = TIDX >> 6, wa = wid >> 1, wb = wid & 1, r = lane & 31, h = lane >> 5;
;   f32x16 acc[AI][BI]; zero_acc<AI, BI>(acc);
;   gemm_tile<AI, BI>(HID + (size_t)m0 * 2816, 2816, W + (size_t)n0 * 2816, 2816, 44, false, acc, lds);
;   const int m0e = m0 + opaque0();
;   const int mr = m0 < TL ? (m0 >> 11) : 8;
.LBB0_473:
	s_or_b64 exec, exec, s[6:7]
	s_mov_b32 s12, s19
	s_mov_b64 s[54:55], s[26:27]
	s_waitcnt lgkmcnt(0)
	s_barrier
	s_add_u32 s8, s54, s12
	s_addc_u32 s9, s55, 0
	s_add_u32 s14, s8, 0x9bb7000
	s_addc_u32 s15, s9, 0
	s_add_u32 s16, s8, 0x1cfb7000
	s_addc_u32 s17, s9, 0
	s_add_u32 s6, s8, 0x2fb7000
	s_addc_u32 s7, s9, 0
	v_readlane_b32 s10, v242, 2
	s_add_u32 s13, s8, s10
	s_addc_u32 s18, s9, 0
	v_readlane_b32 s8, v244, 55
	v_readlane_b32 s9, v244, 56
	s_mov_b64 s[50:51], s[22:23]
	s_mov_b64 s[48:49], s[20:21]
	v_cndmask_b32_e64 v0, 0, 1, s[8:9]
	v_cmp_ne_u32_e64 s[10:11], 1, v0
	s_andn2_b64 vcc, exec, s[8:9]
	s_movk_i32 s48, 0x1600
	v_writelane_b32 v242, s10, 7
	v_readlane_b32 s49, v243, 20
	s_mov_b32 s50, 0x1ffffe0
	s_mov_b64 s[52:53], s[24:25]
	v_writelane_b32 v242, s11, 8
	s_cbranch_vccnz .LBB0_478
	v_readlane_b32 s8, v243, 12
	s_add_u32 s28, s8, s12
	v_readlane_b32 s8, v243, 13
	s_addc_u32 s29, s8, 0
	v_readlane_b32 s8, v243, 16
	s_add_u32 s8, s8, s12
	v_readlane_b32 s9, v243, 17
	s_addc_u32 s9, s9, 0
	v_readlane_b32 s34, v243, 18
	s_cmpk_lg_u32 s92, 0x200
	s_cbranch_scc1 .LBB0_475
	v_and_b32_e32 v0, 31, v178
	v_bfe_u32 v122, v178, 5, 1
	v_bfe_u32 v123, v178, 2, 2
	v_xor_b32_e32 v122, v122, v123
	v_lshlrev_b32_e32 v122, 4, v122
	v_bfe_u32 v123, v178, 7, 1
	v_lshl_add_u32 v123, v123, 6, v0
	v_lshl_add_u32 v142, v123, 6, v122
	v_xor_b32_e32 v143, 32, v142
	v_bfe_u32 v123, v178, 6, 1
	v_lshl_add_u32 v123, v123, 6, v0
	v_lshl_add_u32 v144, v123, 6, v122
	v_add_u32_e32 v144, 0xc000, v144
	v_xor_b32_e32 v145, 32, v144
	v_lshrrev_b32_e32 v0, 2, v178
	v_bfe_u32 v122, v178, 4, 2
	v_and_b32_e32 v123, 3, v178
	v_xor_b32_e32 v122, v122, v123
	v_lshlrev_b32_e32 v122, 4, v122
	v_mul_u32_u24_e32 v0, 0x1600, v0
	v_add_u32_e32 v126, v0, v122
	v_add_u32_e32 v127, 0x58000, v126
	v_add_u32_e32 v128, 0xb0000, v126
	v_add_u32_e32 v129, 0x108000, v126
	v_lshrrev_b32_e32 v0, 6, v178
	s_nop 1
	v_readfirstlane_b32 s68, v0
	s_lshl_b32 s68, s68, 10
	s_and_b32 s71, s96, 7
	s_lshr_b32 s70, s96, 3
	s_and_b32 s72, s70, 7
	s_lshl_b32 s74, s71, 3
	s_add_u32 s72, s72, s74
	s_lshr_b32 s73, s70, 3
	s_mul_i32 s74, s72, 0x160000
	s_add_u32 s64, s14, s74
	s_addc_u32 s65, s15, 0
	s_mul_i32 s74, s73, 0xb0000
	s_add_u32 s66, s16, s74
	s_addc_u32 s67, s17, 0
	s_add_u32 m0, s68, 0
	s_nop 0
	global_load_lds_dwordx4 v126, s[64:65]
	s_add_u32 m0, s68, 4096
	s_nop 0
	global_load_lds_dwordx4 v127, s[64:65]
	s_add_u32 m0, s68, 8192
	s_nop 0
	global_load_lds_dwordx4 v128, s[64:65]
	s_add_u32 m0, s68, 12288
	s_nop 0
	global_load_lds_dwordx4 v129, s[64:65]
	s_add_u32 m0, s68, 49152
	s_nop 0
	global_load_lds_dwordx4 v126, s[66:67]
	s_add_u32 m0, s68, 53248
	s_nop 0
	global_load_lds_dwordx4 v127, s[66:67]
	s_add_u32 s64, s64, 64
	s_addc_u32 s65, s65, 0
	s_add_u32 s66, s66, 64
	s_addc_u32 s67, s67, 0
	s_add_u32 m0, s68, 16384
	s_nop 0
	global_load_lds_dwordx4 v126, s[64:65]
	s_add_u32 m0, s68, 20480
	s_nop 0
	global_load_lds_dwordx4 v127, s[64:65]
	s_add_u32 m0, s68, 24576
	s_nop 0
	global_load_lds_dwordx4 v128, s[64:65]
	s_add_u32 m0, s68, 28672
	s_nop 0
	global_load_lds_dwordx4 v129, s[64:65]
	s_add_u32 m0, s68, 57344
	s_nop 0
	global_load_lds_dwordx4 v126, s[66:67]
	s_add_u32 m0, s68, 61440
	s_nop 0
	global_load_lds_dwordx4 v127, s[66:67]
	s_add_u32 s64, s64, 64
	s_addc_u32 s65, s65, 0
	s_add_u32 s66, s66, 64
	s_addc_u32 s67, s67, 0
	s_waitcnt vmcnt(6)
	s_barrier
	ds_read_b128 v[114:117], v142 offset:0
	ds_read_b128 v[230:233], v144 offset:0
	ds_read_b128 v[234:237], v144 offset:2048
	ds_read_b128 v[118:121], v142 offset:2048
	ds_read_b128 v[134:137], v142 offset:8192
	ds_read_b128 v[138:141], v142 offset:10240
	ds_read_b128 v[238:241], v145 offset:0
	ds_read_b128 v[246:249], v145 offset:2048
	s_add_u32 m0, s68, 32768
	s_nop 0
	global_load_lds_dwordx4 v126, s[64:65]
	s_add_u32 m0, s68, 36864
	s_nop 0
	global_load_lds_dwordx4 v127, s[64:65]
	s_add_u32 m0, s68, 40960
	s_nop 0
	global_load_lds_dwordx4 v128, s[64:65]
	s_add_u32 m0, s68, 45056
	s_nop 0
	global_load_lds_dwordx4 v129, s[64:65]
	s_add_u32 m0, s68, 65664
	s_nop 0
	global_load_lds_dwordx4 v126, s[66:67]
	s_add_u32 m0, s68, 69760
	s_nop 0
	global_load_lds_dwordx4 v127, s[66:67]
	s_add_u32 s64, s64, 64
	s_addc_u32 s65, s65, 0
	s_add_u32 s66, s66, 64
	s_addc_u32 s67, s67, 0
	s_waitcnt lgkmcnt(6)
	v_mfma_f32_32x32x16_bf16 v[2:17], v[114:117], v[230:233], 0
	s_waitcnt lgkmcnt(5)
	v_mfma_f32_32x32x16_bf16 v[18:33], v[114:117], v[234:237], 0
	ds_read_b128 v[114:117], v143 offset:0
	s_waitcnt lgkmcnt(5)
	v_mfma_f32_32x32x16_bf16 v[34:49], v[118:121], v[230:233], 0
	v_mfma_f32_32x32x16_bf16 v[50:65], v[118:121], v[234:237], 0
	ds_read_b128 v[118:121], v143 offset:2048
	s_waitcnt lgkmcnt(5)
	v_mfma_f32_32x32x16_bf16 v[66:81], v[134:137], v[230:233], 0
	v_mfma_f32_32x32x16_bf16 v[82:97], v[134:137], v[234:237], 0
	ds_read_b128 v[134:137], v143 offset:8192
	s_waitcnt lgkmcnt(5)
	v_mfma_f32_32x32x16_bf16 v[98:113], v[138:141], v[230:233], 0
	v_mfma_f32_32x32x16_bf16 v[214:229], v[138:141], v[234:237], 0
	ds_read_b128 v[138:141], v143 offset:10240
	s_waitcnt lgkmcnt(3)
	v_mfma_f32_32x32x16_bf16 v[2:17], v[114:117], v[238:241], v[2:17]
	v_mfma_f32_32x32x16_bf16 v[18:33], v[114:117], v[246:249], v[18:33]
	s_waitcnt lgkmcnt(2)
	v_mfma_f32_32x32x16_bf16 v[34:49], v[118:121], v[238:241], v[34:49]
	v_mfma_f32_32x32x16_bf16 v[50:65], v[118:121], v[246:249], v[50:65]
	s_waitcnt lgkmcnt(1)
	v_mfma_f32_32x32x16_bf16 v[66:81], v[134:137], v[238:241], v[66:81]
	v_mfma_f32_32x32x16_bf16 v[82:97], v[134:137], v[246:249], v[82:97]
	s_waitcnt lgkmcnt(0)
	v_mfma_f32_32x32x16_bf16 v[98:113], v[138:141], v[238:241], v[98:113]
	v_mfma_f32_32x32x16_bf16 v[214:229], v[138:141], v[246:249], v[214:229]
	s_waitcnt vmcnt(6)
	s_barrier
; #define MFMA(a, b, c) __builtin_amdgcn_mfma_f32_32x32x16_bf16((a), (b), (c), 0, 0, 0)
; template <int AI, int BI>
; DI void gemm_tile(const u16* __restrict__ A, int lda, const u16* __restrict__ B, int ldb, int nk, bool swap,
;                   f32x16 (&acc)[AI][BI], char* lds) {
;     ...
;   for (int kt = 0; kt < nk; ++kt) {
;     const char* cur = lds + (kt & 1) * 32768;
;     if (kt + 1 < nk) gemm_stage<AI, BI>(A + (kt + 1) * 64, lda, B + (kt + 1) * 64, ldb, lds + ((kt + 1) & 1) * 32768, tid);
; #pragma unroll
;     for (int ks = 0; ks < 4; ++ks) {
;       const int co = ((ks * 2 + h) ^ sw) << 4;
;       s16x8 fa[AI], fb[BI];
; #pragma unroll
;       for (int i = 0; i < AI; ++i) fa[i] = *(const s16x8*)(cur + offA + i * 4096 + co);
; #pragma unroll
;       for (int i = 0; i < BI; ++i) fb[i] = *(const s16x8*)(cur + offB + i * 4096 + co);
; #pragma unroll
;       for (int i = 0; i < AI; ++i)
; #pragma unroll
;         for (int j = 0; j < BI; ++j) acc[i][j] = MFMA(fa[i], fb[j], acc[i][j]);
;     }
	ds_read_b128 v[114:117], v142 offset:16384
	ds_read_b128 v[230:233], v144 offset:8192
	ds_read_b128 v[234:237], v144 offset:10240
	ds_read_b128 v[118:121], v142 offset:18432
	ds_read_b128 v[134:137], v142 offset:24576
	ds_read_b128 v[138:141], v142 offset:26624
	ds_read_b128 v[238:241], v145 offset:8192
	ds_read_b128 v[246:249], v145 offset:10240
	s_add_u32 m0, s68, 0
	s_nop 0
	global_load_lds_dwordx4 v126, s[64:65]
	s_add_u32 m0, s68, 4096
	s_nop 0
	global_load_lds_dwordx4 v127, s[64:65]
	s_add_u32 m0, s68, 8192
	s_nop 0
	global_load_lds_dwordx4 v128, s[64:65]
	s_add_u32 m0, s68, 12288
	s_nop 0
	global_load_lds_dwordx4 v129, s[64:65]
	s_add_u32 m0, s68, 49152
	s_nop 0
	global_load_lds_dwordx4 v126, s[66:67]
	s_add_u32 m0, s68, 53248
	s_nop 0
	global_load_lds_dwordx4 v127, s[66:67]
	s_add_u32 s64, s64, 64
	s_addc_u32 s65, s65, 0
	s_add_u32 s66, s66, 64
	s_addc_u32 s67, s67, 0
	s_waitcnt lgkmcnt(6)
	v_mfma_f32_32x32x16_bf16 v[2:17], v[114:117], v[230:233], v[2:17]
	s_waitcnt lgkmcnt(5)
	v_mfma_f32_32x32x16_bf16 v[18:33], v[114:117], v[234:237], v[18:33]
	ds_read_b128 v[114:117], v143 offset:16384
	s_waitcnt lgkmcnt(5)
	v_mfma_f32_32x32x16_bf16 v[34:49], v[118:121], v[230:233], v[34:49]
	v_mfma_f32_32x32x16_bf16 v[50:65], v[118:121], v[234:237], v[50:65]
	ds_read_b128 v[118:121], v143 offset:18432
	s_waitcnt lgkmcnt(5)
	v_mfma_f32_32x32x16_bf16 v[66:81], v[134:137], v[230:233], v[66:81]
	v_mfma_f32_32x32x16_bf16 v[82:97], v[134:137], v[234:237], v[82:97]
	ds_read_b128 v[134:137], v143 offset:24576
	s_waitcnt lgkmcnt(5)
	v_mfma_f32_32x32x16_bf16 v[98:113], v[138:141], v[230:233], v[98:113]
	v_mfma_f32_32x32x16_bf16 v[214:229], v[138:141], v[234:237], v[214:229]
	ds_read_b128 v[138:141], v143 offset:26624
	s_waitcnt lgkmcnt(3)
	v_mfma_f32_32x32x16_bf16 v[2:17], v[114:117], v[238:241], v[2:17]
	v_mfma_f32_32x32x16_bf16 v[18:33], v[114:117], v[246:249], v[18:33]
	s_waitcnt lgkmcnt(2)
	v_mfma_f32_32x32x16_bf16 v[34:49], v[118:121], v[238:241], v[34:49]
	v_mfma_f32_32x32x16_bf16 v[50:65], v[118:121], v[246:249], v[50:65]
	s_waitcnt lgkmcnt(1)
	v_mfma_f32_32x32x16_bf16 v[66:81], v[134:137], v[238:241], v[66:81]
	v_mfma_f32_32x32x16_bf16 v[82:97], v[134:137], v[246:249], v[82:97]
	s_waitcnt lgkmcnt(0)
	v_mfma_f32_32x32x16_bf16 v[98:113], v[138:141], v[238:241], v[98:113]
	v_mfma_f32_32x32x16_bf16 v[214:229], v[138:141], v[246:249], v[214:229]
	s_waitcnt vmcnt(6)
	s_barrier
	ds_read_b128 v[114:117], v142 offset:32768
	ds_read_b128 v[230:233], v144 offset:16512
	ds_read_b128 v[234:237], v144 offset:18560
	ds_read_b128 v[118:121], v142 offset:34816
	ds_read_b128 v[134:137], v142 offset:40960
	ds_read_b128 v[138:141], v142 offset:43008
	ds_read_b128 v[238:241], v145 offset:16512
	ds_read_b128 v[246:249], v145 offset:18560
	s_add_u32 m0, s68, 16384
	s_nop 0
	global_load_lds_dwordx4 v126, s[64:65]
	s_add_u32 m0, s68, 20480
	s_nop 0
	global_load_lds_dwordx4 v127, s[64:65]
	s_add_u32 m0, s68, 24576
	s_nop 0
	global_load_lds_dwordx4 v128, s[64:65]
	s_add_u32 m0, s68, 28672
	s_nop 0
	global_load_lds_dwordx4 v129, s[64:65]
	s_add_u32 m0, s68, 57344
	s_nop 0
	global_load_lds_dwordx4 v126, s[66:67]
	s_add_u32 m0, s68, 61440
	s_nop 0
	global_load_lds_dwordx4 v127, s[66:67]
	s_add_u32 s64, s64, 64
	s_addc_u32 s65, s65, 0
	s_add_u32 s66, s66, 64
	s_addc_u32 s67, s67, 0
	s_waitcnt lgkmcnt(6)
	v_mfma_f32_32x32x16_bf16 v[2:17], v[114:117], v[230:233], v[2:17]
	s_waitcnt lgkmcnt(5)
	v_mfma_f32_32x32x16_bf16 v[18:33], v[114:117], v[234:237], v[18:33]
	ds_read_b128 v[114:117], v143 offset:32768
	s_waitcnt lgkmcnt(5)
	v_mfma_f32_32x32x16_bf16 v[34:49], v[118:121], v[230:233], v[34:49]
	v_mfma_f32_32x32x16_bf16 v[50:65], v[118:121], v[234:237], v[50:65]
	ds_read_b128 v[118:121], v143 offset:34816
	s_waitcnt lgkmcnt(5)
	v_mfma_f32_32x32x16_bf16 v[66:81], v[134:137], v[230:233], v[66:81]
	v_mfma_f32_32x32x16_bf16 v[82:97], v[134:137], v[234:237], v[82:97]
	ds_read_b128 v[134:137], v143 offset:40960
	s_waitcnt lgkmcnt(5)
	v_mfma_f32_32x32x16_bf16 v[98:113], v[138:141], v[230:233], v[98:113]
	v_mfma_f32_32x32x16_bf16 v[214:229], v[138:141], v[234:237], v[214:229]
	ds_read_b128 v[138:141], v143 offset:43008
	s_waitcnt lgkmcnt(3)
	v_mfma_f32_32x32x16_bf16 v[2:17], v[114:117], v[238:241], v[2:17]
	v_mfma_f32_32x32x16_bf16 v[18:33], v[114:117], v[246:249], v[18:33]
	s_waitcnt lgkmcnt(2)
	v_mfma_f32_32x32x16_bf16 v[34:49], v[118:121], v[238:241], v[34:49]
	v_mfma_f32_32x32x16_bf16 v[50:65], v[118:121], v[246:249], v[50:65]
	s_waitcnt lgkmcnt(1)
	v_mfma_f32_32x32x16_bf16 v[66:81], v[134:137], v[238:241], v[66:81]
	v_mfma_f32_32x32x16_bf16 v[82:97], v[134:137], v[246:249], v[82:97]
	s_waitcnt lgkmcnt(0)
	v_mfma_f32_32x32x16_bf16 v[98:113], v[138:141], v[238:241], v[98:113]
	v_mfma_f32_32x32x16_bf16 v[214:229], v[138:141], v[246:249], v[214:229]
	s_mov_b32 s69, 27
; #define MFMA(a, b, c) __builtin_amdgcn_mfma_f32_32x32x16_bf16((a), (b), (c), 0, 0, 0)
; template <int AI, int BI>
; DI void gemm_tile(const u16* __restrict__ A, int lda, const u16* __restrict__ B, int ldb, int nk, bool swap,
;                   f32x16 (&acc)[AI][BI], char* lds) {
;     ...
;   for (int kt = 0; kt < nk; ++kt) {
;     const char* cur = lds + (kt & 1) * 32768;
;     if (kt + 1 < nk) gemm_stage<AI, BI>(A + (kt + 1) * 64, lda, B + (kt + 1) * 64, ldb, lds + ((kt + 1) & 1) * 32768, tid);
; #pragma unroll
;     for (int ks = 0; ks < 4; ++ks) {
;       const int co = ((ks * 2 + h) ^ sw) << 4;
;       s16x8 fa[AI], fb[BI];
; #pragma unroll
;       for (int i = 0; i < AI; ++i) fa[i] = *(const s16x8*)(cur + offA + i * 4096 + co);
; #pragma unroll
;       for (int i = 0; i < BI; ++i) fb[i] = *(const s16x8*)(cur + offB + i * 4096 + co);
; #pragma unroll
;       for (int i = 0; i < AI; ++i)
; #pragma unroll
;         for (int j = 0; j < BI; ++j) acc[i][j] = MFMA(fa[i], fb[j], acc[i][j]);
;     }
;     asm volatile("s_waitcnt vmcnt(0)" ::: "memory");
;     __syncthreads();
.Ldn1_kloop:
	s_waitcnt vmcnt(6)
	s_barrier
	ds_read_b128 v[114:117], v142 offset:0
	ds_read_b128 v[230:233], v144 offset:0
	ds_read_b128 v[234:237], v144 offset:2048
	ds_read_b128 v[118:121], v142 offset:2048
	ds_read_b128 v[134:137], v142 offset:8192
	ds_read_b128 v[138:141], v142 offset:10240
	ds_read_b128 v[238:241], v145 offset:0
	ds_read_b128 v[246:249], v145 offset:2048
	s_add_u32 m0, s68, 32768
	s_nop 0
	global_load_lds_dwordx4 v126, s[64:65]
	s_add_u32 m0, s68, 36864
	s_nop 0
	global_load_lds_dwordx4 v127, s[64:65]
	s_add_u32 m0, s68, 40960
	s_nop 0
	global_load_lds_dwordx4 v128, s[64:65]
	s_add_u32 m0, s68, 45056
	s_nop 0
	global_load_lds_dwordx4 v129, s[64:65]
	s_add_u32 m0, s68, 65664
	s_nop 0
	global_load_lds_dwordx4 v126, s[66:67]
	s_add_u32 m0, s68, 69760
	s_nop 0
	global_load_lds_dwordx4 v127, s[66:67]
	s_add_u32 s64, s64, 64
	s_addc_u32 s65, s65, 0
	s_add_u32 s66, s66, 64
	s_addc_u32 s67, s67, 0
	s_waitcnt lgkmcnt(6)
	v_mfma_f32_32x32x16_bf16 v[2:17], v[114:117], v[230:233], v[2:17]
	s_waitcnt lgkmcnt(5)
	v_mfma_f32_32x32x16_bf16 v[18:33], v[114:117], v[234:237], v[18:33]
	ds_read_b128 v[114:117], v143 offset:0
	s_waitcnt lgkmcnt(5)
	v_mfma_f32_32x32x16_bf16 v[34:49], v[118:121], v[230:233], v[34:49]
	v_mfma_f32_32x32x16_bf16 v[50:65], v[118:121], v[234:237], v[50:65]
	ds_read_b128 v[118:121], v143 offset:2048
	s_waitcnt lgkmcnt(5)
	v_mfma_f32_32x32x16_bf16 v[66:81], v[134:137], v[230:233], v[66:81]
	v_mfma_f32_32x32x16_bf16 v[82:97], v[134:137], v[234:237], v[82:97]
	ds_read_b128 v[134:137], v143 offset:8192
	s_waitcnt lgkmcnt(5)
	v_mfma_f32_32x32x16_bf16 v[98:113], v[138:141], v[230:233], v[98:113]
	v_mfma_f32_32x32x16_bf16 v[214:229], v[138:141], v[234:237], v[214:229]
	ds_read_b128 v[138:141], v143 offset:10240
	s_waitcnt lgkmcnt(3)
	v_mfma_f32_32x32x16_bf16 v[2:17], v[114:117], v[238:241], v[2:17]
	v_mfma_f32_32x32x16_bf16 v[18:33], v[114:117], v[246:249], v[18:33]
	s_waitcnt lgkmcnt(2)
	v_mfma_f32_32x32x16_bf16 v[34:49], v[118:121], v[238:241], v[34:49]
	v_mfma_f32_32x32x16_bf16 v[50:65], v[118:121], v[246:249], v[50:65]
	s_waitcnt lgkmcnt(1)
	v_mfma_f32_32x32x16_bf16 v[66:81], v[134:137], v[238:241], v[66:81]
	v_mfma_f32_32x32x16_bf16 v[82:97], v[134:137], v[246:249], v[82:97]
	s_waitcnt lgkmcnt(0)
	v_mfma_f32_32x32x16_bf16 v[98:113], v[138:141], v[238:241], v[98:113]
	v_mfma_f32_32x32x16_bf16 v[214:229], v[138:141], v[246:249], v[214:229]
	s_waitcnt vmcnt(6)
	s_barrier
	ds_read_b128 v[114:117], v142 offset:16384
	ds_read_b128 v[230:233], v144 offset:8192
	ds_read_b128 v[234:237], v144 offset:10240
	ds_read_b128 v[118:121], v142 offset:18432
	ds_read_b128 v[134:137], v142 offset:24576
	ds_read_b128 v[138:141], v142 offset:26624
	ds_read_b128 v[238:241], v145 offset:8192
	ds_read_b128 v[246:249], v145 offset:10240
	s_add_u32 m0, s68, 0
	s_nop 0
	global_load_lds_dwordx4 v126, s[64:65]
	s_add_u32 m0, s68, 4096
	s_nop 0
	global_load_lds_dwordx4 v127, s[64:65]
	s_add_u32 m0, s68, 8192
	s_nop 0
	global_load_lds_dwordx4 v128, s[64:65]
	s_add_u32 m0, s68, 12288
	s_nop 0
	global_load_lds_dwordx4 v129, s[64:65]
	s_add_u32 m0, s68, 49152
	s_nop 0
	global_load_lds_dwordx4 v126, s[66:67]
	s_add_u32 m0, s68, 53248
	s_nop 0
	global_load_lds_dwordx4 v127, s[66:67]
	s_add_u32 s64, s64, 64
	s_addc_u32 s65, s65, 0
	s_add_u32 s66, s66, 64
	s_addc_u32 s67, s67, 0
	s_waitcnt lgkmcnt(6)
	v_mfma_f32_32x32x16_bf16 v[2:17], v[114:117], v[230:233], v[2:17]
	s_waitcnt lgkmcnt(5)
	v_mfma_f32_32x32x16_bf16 v[18:33], v[114:117], v[234:237], v[18:33]
	ds_read_b128 v[114:117], v143 offset:16384
	s_waitcnt lgkmcnt(5)
	v_mfma_f32_32x32x16_bf16 v[34:49], v[118:121], v[230:233], v[34:49]
	v_mfma_f32_32x32x16_bf16 v[50:65], v[118:121], v[234:237], v[50:65]
	ds_read_b128 v[118:121], v143 offset:18432
	s_waitcnt lgkmcnt(5)
	v_mfma_f32_32x32x16_bf16 v[66:81], v[134:137], v[230:233], v[66:81]
	v_mfma_f32_32x32x16_bf16 v[82:97], v[134:137], v[234:237], v[82:97]
	ds_read_b128 v[134:137], v143 offset:24576
	s_waitcnt lgkmcnt(5)
	v_mfma_f32_32x32x16_bf16 v[98:113], v[138:141], v[230:233], v[98:113]
	v_mfma_f32_32x32x16_bf16 v[214:229], v[138:141], v[234:237], v[214:229]
	ds_read_b128 v[138:141], v143 offset:26624
	s_waitcnt lgkmcnt(3)
	v_mfma_f32_32x32x16_bf16 v[2:17], v[114:117], v[238:241], v[2:17]
	v_mfma_f32_32x32x16_bf16 v[18:33], v[114:117], v[246:249], v[18:33]
	s_waitcnt lgkmcnt(2)
	v_mfma_f32_32x32x16_bf16 v[34:49], v[118:121], v[238:241], v[34:49]
	v_mfma_f32_32x32x16_bf16 v[50:65], v[118:121], v[246:249], v[50:65]
	s_waitcnt lgkmcnt(1)
	v_mfma_f32_32x32x16_bf16 v[66:81], v[134:137], v[238:241], v[66:81]
	v_mfma_f32_32x32x16_bf16 v[82:97], v[134:137], v[246:249], v[82:97]
	s_waitcnt lgkmcnt(0)
	v_mfma_f32_32x32x16_bf16 v[98:113], v[138:141], v[238:241], v[98:113]
	v_mfma_f32_32x32x16_bf16 v[214:229], v[138:141], v[246:249], v[214:229]
	s_waitcnt vmcnt(6)
	s_barrier
; #define MFMA(a, b, c) __builtin_amdgcn_mfma_f32_32x32x16_bf16((a), (b), (c), 0, 0, 0)
; template <int AI, int BI>
; DI void gemm_tile(const u16* __restrict__ A, int lda, const u16* __restrict__ B, int ldb, int nk, bool swap,
;                   f32x16 (&acc)[AI][BI], char* lds) {
;     ...
;   for (int kt = 0; kt < nk; ++kt) {
;     const char* cur = lds + (kt & 1) * 32768;
;     if (kt + 1 < nk) gemm_stage<AI, BI>(A + (kt + 1) * 64, lda, B + (kt + 1) * 64, ldb, lds + ((kt + 1) & 1) * 32768, tid);
; #pragma unroll
;     for (int ks = 0; ks < 4; ++ks) {
;       const int co = ((ks * 2 + h) ^ sw) << 4;
;       s16x8 fa[AI], fb[BI];
; #pragma unroll
;       for (int i = 0; i < AI; ++i) fa[i] = *(const s16x8*)(cur + offA + i * 4096 + co);
; #pragma unroll
;       for (int i = 0; i < BI; ++i) fb[i] = *(const s16x8*)(cur + offB + i * 4096 + co);
; #pragma unroll
;       for (int i = 0; i < AI; ++i)
; #pragma unroll
;         for (int j = 0; j < BI; ++j) acc[i][j] = MFMA(fa[i], fb[j], acc[i][j]);
;     }
;     asm volatile("s_waitcnt vmcnt(0)" ::: "memory");
;     __syncthreads();
;   }
	ds_read_b128 v[114:117], v142 offset:32768
	ds_read_b128 v[230:233], v144 offset:16512
	ds_read_b128 v[234:237], v144 offset:18560
	ds_read_b128 v[118:121], v142 offset:34816
	ds_read_b128 v[134:137], v142 offset:40960
	ds_read_b128 v[138:141], v142 offset:43008
	ds_read_b128 v[238:241], v145 offset:16512
	ds_read_b128 v[246:249], v145 offset:18560
	s_add_u32 m0, s68, 16384
	s_nop 0
	global_load_lds_dwordx4 v126, s[64:65]
	s_add_u32 m0, s68, 20480
	s_nop 0
	global_load_lds_dwordx4 v127, s[64:65]
	s_add_u32 m0, s68, 24576
	s_nop 0
	global_load_lds_dwordx4 v128, s[64:65]
	s_add_u32 m0, s68, 28672
	s_nop 0
	global_load_lds_dwordx4 v129, s[64:65]
	s_add_u32 m0, s68, 57344
	s_nop 0
	global_load_lds_dwordx4 v126, s[66:67]
	s_add_u32 m0, s68, 61440
	s_nop 0
	global_load_lds_dwordx4 v127, s[66:67]
	s_add_u32 s64, s64, 64
	s_addc_u32 s65, s65, 0
	s_add_u32 s66, s66, 64
	s_addc_u32 s67, s67, 0
	s_waitcnt lgkmcnt(6)
	v_mfma_f32_32x32x16_bf16 v[2:17], v[114:117], v[230:233], v[2:17]
	s_waitcnt lgkmcnt(5)
	v_mfma_f32_32x32x16_bf16 v[18:33], v[114:117], v[234:237], v[18:33]
	ds_read_b128 v[114:117], v143 offset:32768
	s_waitcnt lgkmcnt(5)
	v_mfma_f32_32x32x16_bf16 v[34:49], v[118:121], v[230:233], v[34:49]
	v_mfma_f32_32x32x16_bf16 v[50:65], v[118:121], v[234:237], v[50:65]
	ds_read_b128 v[118:121], v143 offset:34816
	s_waitcnt lgkmcnt(5)
	v_mfma_f32_32x32x16_bf16 v[66:81], v[134:137], v[230:233], v[66:81]
	v_mfma_f32_32x32x16_bf16 v[82:97], v[134:137], v[234:237], v[82:97]
	ds_read_b128 v[134:137], v143 offset:40960
	s_waitcnt lgkmcnt(5)
	v_mfma_f32_32x32x16_bf16 v[98:113], v[138:141], v[230:233], v[98:113]
	v_mfma_f32_32x32x16_bf16 v[214:229], v[138:141], v[234:237], v[214:229]
	ds_read_b128 v[138:141], v143 offset:43008
	s_waitcnt lgkmcnt(3)
	v_mfma_f32_32x32x16_bf16 v[2:17], v[114:117], v[238:241], v[2:17]
	v_mfma_f32_32x32x16_bf16 v[18:33], v[114:117], v[246:249], v[18:33]
	s_waitcnt lgkmcnt(2)
	v_mfma_f32_32x32x16_bf16 v[34:49], v[118:121], v[238:241], v[34:49]
	v_mfma_f32_32x32x16_bf16 v[50:65], v[118:121], v[246:249], v[50:65]
	s_waitcnt lgkmcnt(1)
	v_mfma_f32_32x32x16_bf16 v[66:81], v[134:137], v[238:241], v[66:81]
	v_mfma_f32_32x32x16_bf16 v[82:97], v[134:137], v[246:249], v[82:97]
	s_waitcnt lgkmcnt(0)
	v_mfma_f32_32x32x16_bf16 v[98:113], v[138:141], v[238:241], v[98:113]
	v_mfma_f32_32x32x16_bf16 v[214:229], v[138:141], v[246:249], v[214:229]
	s_sub_u32 s69, s69, 1
	s_cmp_lg_u32 s69, 0
	s_cbranch_scc1 .Ldn1_kloop
	s_waitcnt vmcnt(6)
	s_barrier
	ds_read_b128 v[114:117], v142 offset:0
	ds_read_b128 v[230:233], v144 offset:0
	ds_read_b128 v[234:237], v144 offset:2048
	ds_read_b128 v[118:121], v142 offset:2048
	ds_read_b128 v[134:137], v142 offset:8192
	ds_read_b128 v[138:141], v142 offset:10240
	ds_read_b128 v[238:241], v145 offset:0
	ds_read_b128 v[246:249], v145 offset:2048
	s_add_u32 m0, s68, 32768
	s_nop 0
	global_load_lds_dwordx4 v126, s[64:65]
	s_add_u32 m0, s68, 36864
	s_nop 0
	global_load_lds_dwordx4 v127, s[64:65]
	s_add_u32 m0, s68, 40960
	s_nop 0
	global_load_lds_dwordx4 v128, s[64:65]
	s_add_u32 m0, s68, 45056
	s_nop 0
	global_load_lds_dwordx4 v129, s[64:65]
	s_add_u32 m0, s68, 65664
	s_nop 0
	global_load_lds_dwordx4 v126, s[66:67]
	s_add_u32 m0, s68, 69760
	s_nop 0
	global_load_lds_dwordx4 v127, s[66:67]
	s_add_u32 s64, s64, 64
	s_addc_u32 s65, s65, 0
	s_add_u32 s66, s66, 64
	s_addc_u32 s67, s67, 0
	s_waitcnt lgkmcnt(6)
	v_mfma_f32_32x32x16_bf16 v[2:17], v[114:117], v[230:233], v[2:17]
	s_waitcnt lgkmcnt(5)
	v_mfma_f32_32x32x16_bf16 v[18:33], v[114:117], v[234:237], v[18:33]
	ds_read_b128 v[114:117], v143 offset:0
	s_waitcnt lgkmcnt(5)
	v_mfma_f32_32x32x16_bf16 v[34:49], v[118:121], v[230:233], v[34:49]
	v_mfma_f32_32x32x16_bf16 v[50:65], v[118:121], v[234:237], v[50:65]
	ds_read_b128 v[118:121], v143 offset:2048
	s_waitcnt lgkmcnt(5)
	v_mfma_f32_32x32x16_bf16 v[66:81], v[134:137], v[230:233], v[66:81]
	v_mfma_f32_32x32x16_bf16 v[82:97], v[134:137], v[234:237], v[82:97]
	ds_read_b128 v[134:137], v143 offset:8192
	s_waitcnt lgkmcnt(5)
	v_mfma_f32_32x32x16_bf16 v[98:113], v[138:141], v[230:233], v[98:113]
	v_mfma_f32_32x32x16_bf16 v[214:229], v[138:141], v[234:237], v[214:229]
	ds_read_b128 v[138:141], v143 offset:10240
	s_waitcnt lgkmcnt(3)
	v_mfma_f32_32x32x16_bf16 v[2:17], v[114:117], v[238:241], v[2:17]
	v_mfma_f32_32x32x16_bf16 v[18:33], v[114:117], v[246:249], v[18:33]
	s_waitcnt lgkmcnt(2)
	v_mfma_f32_32x32x16_bf16 v[34:49], v[118:121], v[238:241], v[34:49]
	v_mfma_f32_32x32x16_bf16 v[50:65], v[118:121], v[246:249], v[50:65]
	s_waitcnt lgkmcnt(1)
	v_mfma_f32_32x32x16_bf16 v[66:81], v[134:137], v[238:241], v[66:81]
	v_mfma_f32_32x32x16_bf16 v[82:97], v[134:137], v[246:249], v[82:97]
	s_waitcnt lgkmcnt(0)
	v_mfma_f32_32x32x16_bf16 v[98:113], v[138:141], v[238:241], v[98:113]
	v_mfma_f32_32x32x16_bf16 v[214:229], v[138:141], v[246:249], v[214:229]
	s_waitcnt vmcnt(6)
	s_barrier
; #define MFMA(a, b, c) __builtin_amdgcn_mfma_f32_32x32x16_bf16((a), (b), (c), 0, 0, 0)
; template <int AI, int BI>
; DI void gemm_tile(const u16* __restrict__ A, int lda, const u16* __restrict__ B, int ldb, int nk, bool swap,
;                   f32x16 (&acc)[AI][BI], char* lds) {
;     ...
;   for (int kt = 0; kt < nk; ++kt) {
;     const char* cur = lds + (kt & 1) * 32768;
;     if (kt + 1 < nk) gemm_stage<AI, BI>(A + (kt + 1) * 64, lda, B + (kt + 1) * 64, ldb, lds + ((kt + 1) & 1) * 32768, tid);
; #pragma unroll
;     for (int ks = 0; ks < 4; ++ks) {
;       const int co = ((ks * 2 + h) ^ sw) << 4;
;       s16x8 fa[AI], fb[BI];
; #pragma unroll
;       for (int i = 0; i < AI; ++i) fa[i] = *(const s16x8*)(cur + offA + i * 4096 + co);
; #pragma unroll
;       for (int i = 0; i < BI; ++i) fb[i] = *(const s16x8*)(cur + offB + i * 4096 + co);
; #pragma unroll
;       for (int i = 0; i < AI; ++i)
; #pragma unroll
;         for (int j = 0; j < BI; ++j) acc[i][j] = MFMA(fa[i], fb[j], acc[i][j]);
;     }
;     asm volatile("s_waitcnt vmcnt(0)" ::: "memory");
;     __syncthreads();
;   }
	ds_read_b128 v[114:117], v142 offset:16384
	ds_read_b128 v[230:233], v144 offset:8192
	ds_read_b128 v[234:237], v144 offset:10240
	ds_read_b128 v[118:121], v142 offset:18432
	ds_read_b128 v[134:137], v142 offset:24576
	ds_read_b128 v[138:141], v142 offset:26624
	ds_read_b128 v[238:241], v145 offset:8192
	ds_read_b128 v[246:249], v145 offset:10240
	s_add_u32 m0, s68, 0
	s_nop 0
	global_load_lds_dwordx4 v126, s[64:65]
	s_add_u32 m0, s68, 4096
	s_nop 0
	global_load_lds_dwordx4 v127, s[64:65]
	s_add_u32 m0, s68, 8192
	s_nop 0
	global_load_lds_dwordx4 v128, s[64:65]
	s_add_u32 m0, s68, 12288
	s_nop 0
	global_load_lds_dwordx4 v129, s[64:65]
	s_add_u32 m0, s68, 49152
	s_nop 0
	global_load_lds_dwordx4 v126, s[66:67]
	s_add_u32 m0, s68, 53248
	s_nop 0
	global_load_lds_dwordx4 v127, s[66:67]
	s_add_u32 s64, s64, 64
	s_addc_u32 s65, s65, 0
	s_add_u32 s66, s66, 64
	s_addc_u32 s67, s67, 0
	s_waitcnt lgkmcnt(6)
	v_mfma_f32_32x32x16_bf16 v[2:17], v[114:117], v[230:233], v[2:17]
	s_waitcnt lgkmcnt(5)
	v_mfma_f32_32x32x16_bf16 v[18:33], v[114:117], v[234:237], v[18:33]
	ds_read_b128 v[114:117], v143 offset:16384
	s_waitcnt lgkmcnt(5)
	v_mfma_f32_32x32x16_bf16 v[34:49], v[118:121], v[230:233], v[34:49]
	v_mfma_f32_32x32x16_bf16 v[50:65], v[118:121], v[234:237], v[50:65]
	ds_read_b128 v[118:121], v143 offset:18432
	s_waitcnt lgkmcnt(5)
	v_mfma_f32_32x32x16_bf16 v[66:81], v[134:137], v[230:233], v[66:81]
	v_mfma_f32_32x32x16_bf16 v[82:97], v[134:137], v[234:237], v[82:97]
	ds_read_b128 v[134:137], v143 offset:24576
	s_waitcnt lgkmcnt(5)
	v_mfma_f32_32x32x16_bf16 v[98:113], v[138:141], v[230:233], v[98:113]
	v_mfma_f32_32x32x16_bf16 v[214:229], v[138:141], v[234:237], v[214:229]
	ds_read_b128 v[138:141], v143 offset:26624
	s_waitcnt lgkmcnt(3)
	v_mfma_f32_32x32x16_bf16 v[2:17], v[114:117], v[238:241], v[2:17]
	v_mfma_f32_32x32x16_bf16 v[18:33], v[114:117], v[246:249], v[18:33]
	s_waitcnt lgkmcnt(2)
	v_mfma_f32_32x32x16_bf16 v[34:49], v[118:121], v[238:241], v[34:49]
	v_mfma_f32_32x32x16_bf16 v[50:65], v[118:121], v[246:249], v[50:65]
	s_waitcnt lgkmcnt(1)
	v_mfma_f32_32x32x16_bf16 v[66:81], v[134:137], v[238:241], v[66:81]
	v_mfma_f32_32x32x16_bf16 v[82:97], v[134:137], v[246:249], v[82:97]
	s_waitcnt lgkmcnt(0)
	v_mfma_f32_32x32x16_bf16 v[98:113], v[138:141], v[238:241], v[98:113]
	v_mfma_f32_32x32x16_bf16 v[214:229], v[138:141], v[246:249], v[214:229]
	s_waitcnt vmcnt(6)
	s_barrier
	ds_read_b128 v[114:117], v142 offset:32768
	ds_read_b128 v[230:233], v144 offset:16512
	ds_read_b128 v[234:237], v144 offset:18560
	ds_read_b128 v[118:121], v142 offset:34816
	ds_read_b128 v[134:137], v142 offset:40960
	ds_read_b128 v[138:141], v142 offset:43008
	ds_read_b128 v[238:241], v145 offset:16512
	ds_read_b128 v[246:249], v145 offset:18560
	s_waitcnt lgkmcnt(6)
	v_mfma_f32_32x32x16_bf16 v[2:17], v[114:117], v[230:233], v[2:17]
	s_waitcnt lgkmcnt(5)
	v_mfma_f32_32x32x16_bf16 v[18:33], v[114:117], v[234:237], v[18:33]
	ds_read_b128 v[114:117], v143 offset:32768
	s_waitcnt lgkmcnt(5)
	v_mfma_f32_32x32x16_bf16 v[34:49], v[118:121], v[230:233], v[34:49]
	v_mfma_f32_32x32x16_bf16 v[50:65], v[118:121], v[234:237], v[50:65]
	ds_read_b128 v[118:121], v143 offset:34816
	s_waitcnt lgkmcnt(5)
	v_mfma_f32_32x32x16_bf16 v[66:81], v[134:137], v[230:233], v[66:81]
	v_mfma_f32_32x32x16_bf16 v[82:97], v[134:137], v[234:237], v[82:97]
	ds_read_b128 v[134:137], v143 offset:40960
	s_waitcnt lgkmcnt(5)
	v_mfma_f32_32x32x16_bf16 v[98:113], v[138:141], v[230:233], v[98:113]
	v_mfma_f32_32x32x16_bf16 v[214:229], v[138:141], v[234:237], v[214:229]
	ds_read_b128 v[138:141], v143 offset:43008
	s_waitcnt lgkmcnt(3)
	v_mfma_f32_32x32x16_bf16 v[2:17], v[114:117], v[238:241], v[2:17]
	v_mfma_f32_32x32x16_bf16 v[18:33], v[114:117], v[246:249], v[18:33]
	s_waitcnt lgkmcnt(2)
	v_mfma_f32_32x32x16_bf16 v[34:49], v[118:121], v[238:241], v[34:49]
	v_mfma_f32_32x32x16_bf16 v[50:65], v[118:121], v[246:249], v[50:65]
	s_waitcnt lgkmcnt(1)
	v_mfma_f32_32x32x16_bf16 v[66:81], v[134:137], v[238:241], v[66:81]
	v_mfma_f32_32x32x16_bf16 v[82:97], v[134:137], v[246:249], v[82:97]
	s_waitcnt lgkmcnt(0)
	v_mfma_f32_32x32x16_bf16 v[98:113], v[138:141], v[238:241], v[98:113]
	v_mfma_f32_32x32x16_bf16 v[214:229], v[138:141], v[246:249], v[214:229]
	s_waitcnt vmcnt(0)
	s_barrier
	ds_read_b128 v[114:117], v142 offset:0
	ds_read_b128 v[230:233], v144 offset:0
	ds_read_b128 v[234:237], v144 offset:2048
	ds_read_b128 v[118:121], v142 offset:2048
	ds_read_b128 v[134:137], v142 offset:8192
	ds_read_b128 v[138:141], v142 offset:10240
	ds_read_b128 v[238:241], v145 offset:0
	ds_read_b128 v[246:249], v145 offset:2048
	s_waitcnt lgkmcnt(6)
	v_mfma_f32_32x32x16_bf16 v[2:17], v[114:117], v[230:233], v[2:17]
	s_waitcnt lgkmcnt(5)
	v_mfma_f32_32x32x16_bf16 v[18:33], v[114:117], v[234:237], v[18:33]
	ds_read_b128 v[114:117], v143 offset:0
	s_waitcnt lgkmcnt(5)
	v_mfma_f32_32x32x16_bf16 v[34:49], v[118:121], v[230:233], v[34:49]
	v_mfma_f32_32x32x16_bf16 v[50:65], v[118:121], v[234:237], v[50:65]
	ds_read_b128 v[118:121], v143 offset:2048
	s_waitcnt lgkmcnt(5)
	v_mfma_f32_32x32x16_bf16 v[66:81], v[134:137], v[230:233], v[66:81]
	v_mfma_f32_32x32x16_bf16 v[82:97], v[134:137], v[234:237], v[82:97]
	ds_read_b128 v[134:137], v143 offset:8192
	s_waitcnt lgkmcnt(5)
	v_mfma_f32_32x32x16_bf16 v[98:113], v[138:141], v[230:233], v[98:113]
	v_mfma_f32_32x32x16_bf16 v[214:229], v[138:141], v[234:237], v[214:229]
	ds_read_b128 v[138:141], v143 offset:10240
	s_waitcnt lgkmcnt(3)
	v_mfma_f32_32x32x16_bf16 v[2:17], v[114:117], v[238:241], v[2:17]
	v_mfma_f32_32x32x16_bf16 v[18:33], v[114:117], v[246:249], v[18:33]
	s_waitcnt lgkmcnt(2)
	v_mfma_f32_32x32x16_bf16 v[34:49], v[118:121], v[238:241], v[34:49]
	v_mfma_f32_32x32x16_bf16 v[50:65], v[118:121], v[246:249], v[50:65]
	s_waitcnt lgkmcnt(1)
	v_mfma_f32_32x32x16_bf16 v[66:81], v[134:137], v[238:241], v[66:81]
	v_mfma_f32_32x32x16_bf16 v[82:97], v[134:137], v[246:249], v[82:97]
	s_waitcnt lgkmcnt(0)
	v_mfma_f32_32x32x16_bf16 v[98:113], v[138:141], v[238:241], v[98:113]
	v_mfma_f32_32x32x16_bf16 v[214:229], v[138:141], v[246:249], v[214:229]
	s_nop 7
	s_nop 7
	s_barrier
; #define GAS __attribute__((address_space(1)))
; DI int opaque0() { int z = 0; asm volatile("" : "+v"(z)); return z; }
; template <int AI, int BI>
; DI void dn_tile(const Params& p, char* wsb, int layer, int sub, bool final_out, int m0, int n0, char* lds) {
;     ...
;   const int m0e = m0 + opaque0();
;   const int mr = m0 < TL ? (m0 >> 11) : 8;
;   const float* gate = mods + (size_t)mr * 9216 + (2 + 6 * sub) * 1024;
;   GAS float* xsu = uptr(xs);
;   GAS float* outu = uptr(p.out);
; #pragma unroll
;   for (int bi = 0; bi < BI; ++bi) {
;     const int n = n0 + wb * 32 * BI + bi * 32 + r;
;     const float gv = 0.5f * gate[n];
;     const unsigned ib = (unsigned)((m0e + wa * 32 * AI + 4 * h) * 1024 + n);
; #pragma unroll
;     for (int ai = 0; ai < AI; ++ai)
; #pragma unroll
;       for (int reg = 0; reg < 16; ++reg) {
;         const unsigned idx = ib + (unsigned)((ai * 32 + (reg & 3) + 8 * (reg >> 2)) * 1024);
;         float v = xsu[idx] + gv * acc[ai][bi][reg];
;         if (final_out) outu[idx] = v; else xsu[idx] = v;
;         if ((reg & 7) == 7) __builtin_amdgcn_sched_barrier(0);
;       }
;   }
	v_and_b32_e32 v0, 31, v178
	v_and_b32_e32 v123, 64, v178
	v_or_b32_e32 v123, v123, v0
	v_bfe_u32 v0, v178, 5, 1
	v_bfe_u32 v122, v178, 7, 1
	v_lshlrev_b32_e32 v122, 6, v122
	v_lshl_add_u32 v122, v0, 2, v122
	v_lshl_add_u32 v122, v122, 10, v123
	v_lshlrev_b32_e32 v122, 2, v122
	s_lshl_b32 s74, s73, 7
	v_add_u32_e32 v123, s74, v123
	v_lshlrev_b32_e32 v123, 2, v123
	s_lshr_b32 s75, s72, 3
	s_mul_i32 s75, s75, 0x9000
	s_add_u32 s76, s13, s75
	s_addc_u32 s77, s18, 0
	s_add_u32 s76, s76, 0x6000
	s_addc_u32 s77, s77, 0
	global_load_dword v124, v123, s[76:77]
	global_load_dword v142, v123, s[76:77] offset:128
	s_lshl_b32 s75, s72, 20
	s_lshl_b32 s74, s73, 9
	s_add_u32 s75, s75, s74
	s_add_u32 s80, s6, s75
	s_addc_u32 s81, s7, 0
	s_waitcnt vmcnt(0)
	v_mul_f32_e32 v124, 0.5, v124
	v_mul_f32_e32 v142, 0.5, v142
	s_add_u32 s52, s80, 0
	s_addc_u32 s53, s81, 0
	global_load_dword v114, v122, s[52:53]
	global_load_dword v115, v122, s[52:53] offset:128
	s_add_u32 s52, s52, 4096
	s_addc_u32 s53, s53, 0
	global_load_dword v116, v122, s[52:53]
	global_load_dword v117, v122, s[52:53] offset:128
	s_add_u32 s52, s52, 4096
	s_addc_u32 s53, s53, 0
	global_load_dword v118, v122, s[52:53]
	global_load_dword v119, v122, s[52:53] offset:128
	s_add_u32 s52, s52, 4096
	s_addc_u32 s53, s53, 0
	global_load_dword v120, v122, s[52:53]
	global_load_dword v121, v122, s[52:53] offset:128
	s_add_u32 s52, s52, 20480
	s_addc_u32 s53, s53, 0
	global_load_dword v134, v122, s[52:53]
	global_load_dword v135, v122, s[52:53] offset:128
	s_add_u32 s52, s52, 4096
	s_addc_u32 s53, s53, 0
	global_load_dword v136, v122, s[52:53]
	global_load_dword v137, v122, s[52:53] offset:128
	s_add_u32 s52, s52, 4096
	s_addc_u32 s53, s53, 0
	global_load_dword v138, v122, s[52:53]
	global_load_dword v139, v122, s[52:53] offset:128
	s_add_u32 s52, s52, 4096
	s_addc_u32 s53, s53, 0
	global_load_dword v140, v122, s[52:53]
	global_load_dword v141, v122, s[52:53] offset:128
	s_waitcnt vmcnt(0)
	v_fmac_f32_e32 v114, v2, v124
	v_fmac_f32_e32 v115, v18, v142
	v_fmac_f32_e32 v116, v3, v124
	v_fmac_f32_e32 v117, v19, v142
	v_fmac_f32_e32 v118, v4, v124
	v_fmac_f32_e32 v119, v20, v142
	v_fmac_f32_e32 v120, v5, v124
	v_fmac_f32_e32 v121, v21, v142
	v_fmac_f32_e32 v134, v6, v124
	v_fmac_f32_e32 v135, v22, v142
	v_fmac_f32_e32 v136, v7, v124
	v_fmac_f32_e32 v137, v23, v142
	v_fmac_f32_e32 v138, v8, v124
	v_fmac_f32_e32 v139, v24, v142
	v_fmac_f32_e32 v140, v9, v124
	v_fmac_f32_e32 v141, v25, v142
	s_add_u32 s52, s80, 0
	s_addc_u32 s53, s81, 0
	global_store_dword v122, v114, s[52:53]
	global_store_dword v122, v115, s[52:53] offset:128
	s_add_u32 s52, s52, 4096
	s_addc_u32 s53, s53, 0
	global_store_dword v122, v116, s[52:53]
	global_store_dword v122, v117, s[52:53] offset:128
	s_add_u32 s52, s52, 4096
	s_addc_u32 s53, s53, 0
	global_store_dword v122, v118, s[52:53]
	global_store_dword v122, v119, s[52:53] offset:128
	s_add_u32 s52, s52, 4096
	s_addc_u32 s53, s53, 0
	global_store_dword v122, v120, s[52:53]
	global_store_dword v122, v121, s[52:53] offset:128
	s_add_u32 s52, s52, 20480
	s_addc_u32 s53, s53, 0
	global_store_dword v122, v134, s[52:53]
	global_store_dword v122, v135, s[52:53] offset:128
	s_add_u32 s52, s52, 4096
	s_addc_u32 s53, s53, 0
	global_store_dword v122, v136, s[52:53]
	global_store_dword v122, v137, s[52:53] offset:128
	s_add_u32 s52, s52, 4096
	s_addc_u32 s53, s53, 0
	global_store_dword v122, v138, s[52:53]
	global_store_dword v122, v139, s[52:53] offset:128
	s_add_u32 s52, s52, 4096
	s_addc_u32 s53, s53, 0
	global_store_dword v122, v140, s[52:53]
	global_store_dword v122, v141, s[52:53] offset:128
	s_add_u32 s52, s80, 65536
	s_addc_u32 s53, s81, 0
	global_load_dword v114, v122, s[52:53]
	global_load_dword v115, v122, s[52:53] offset:128
	s_add_u32 s52, s52, 4096
	s_addc_u32 s53, s53, 0
	global_load_dword v116, v122, s[52:53]
	global_load_dword v117, v122, s[52:53] offset:128
	s_add_u32 s52, s52, 4096
	s_addc_u32 s53, s53, 0
	global_load_dword v118, v122, s[52:53]
	global_load_dword v119, v122, s[52:53] offset:128
	s_add_u32 s52, s52, 4096
	s_addc_u32 s53, s53, 0
	global_load_dword v120, v122, s[52:53]
	global_load_dword v121, v122, s[52:53] offset:128
	s_add_u32 s52, s52, 20480
	s_addc_u32 s53, s53, 0
	global_load_dword v134, v122, s[52:53]
	global_load_dword v135, v122, s[52:53] offset:128
	s_add_u32 s52, s52, 4096
	s_addc_u32 s53, s53, 0
	global_load_dword v136, v122, s[52:53]
	global_load_dword v137, v122, s[52:53] offset:128
	s_add_u32 s52, s52, 4096
	s_addc_u32 s53, s53, 0
	global_load_dword v138, v122, s[52:53]
	global_load_dword v139, v122, s[52:53] offset:128
	s_add_u32 s52, s52, 4096
	s_addc_u32 s53, s53, 0
	global_load_dword v140, v122, s[52:53]
	global_load_dword v141, v122, s[52:53] offset:128
	s_waitcnt vmcnt(0)
; template <int AI, int BI>
; DI void dn_tile(const Params& p, char* wsb, int layer, int sub, bool final_out, int m0, int n0, char* lds) {
;     ...
; #pragma unroll
;   for (int bi = 0; bi < BI; ++bi) {
;     const int n = n0 + wb * 32 * BI + bi * 32 + r;
;     const float gv = 0.5f * gate[n];
;     const unsigned ib = (unsigned)((m0e + wa * 32 * AI + 4 * h) * 1024 + n);
; #pragma unroll
;     for (int ai = 0; ai < AI; ++ai)
; #pragma unroll
;       for (int reg = 0; reg < 16; ++reg) {
;         const unsigned idx = ib + (unsigned)((ai * 32 + (reg & 3) + 8 * (reg >> 2)) * 1024);
;         float v = xsu[idx] + gv * acc[ai][bi][reg];
;         if (final_out) outu[idx] = v; else xsu[idx] = v;
;         if ((reg & 7) == 7) __builtin_amdgcn_sched_barrier(0);
;       }
;   }
	v_fmac_f32_e32 v114, v10, v124
	v_fmac_f32_e32 v115, v26, v142
	v_fmac_f32_e32 v116, v11, v124
	v_fmac_f32_e32 v117, v27, v142
	v_fmac_f32_e32 v118, v12, v124
	v_fmac_f32_e32 v119, v28, v142
	v_fmac_f32_e32 v120, v13, v124
	v_fmac_f32_e32 v121, v29, v142
	v_fmac_f32_e32 v134, v14, v124
	v_fmac_f32_e32 v135, v30, v142
	v_fmac_f32_e32 v136, v15, v124
	v_fmac_f32_e32 v137, v31, v142
	v_fmac_f32_e32 v138, v16, v124
	v_fmac_f32_e32 v139, v32, v142
	v_fmac_f32_e32 v140, v17, v124
	v_fmac_f32_e32 v141, v33, v142
	s_add_u32 s52, s80, 65536
	s_addc_u32 s53, s81, 0
	global_store_dword v122, v114, s[52:53]
	global_store_dword v122, v115, s[52:53] offset:128
	s_add_u32 s52, s52, 4096
	s_addc_u32 s53, s53, 0
	global_store_dword v122, v116, s[52:53]
	global_store_dword v122, v117, s[52:53] offset:128
	s_add_u32 s52, s52, 4096
	s_addc_u32 s53, s53, 0
	global_store_dword v122, v118, s[52:53]
	global_store_dword v122, v119, s[52:53] offset:128
	s_add_u32 s52, s52, 4096
	s_addc_u32 s53, s53, 0
	global_store_dword v122, v120, s[52:53]
	global_store_dword v122, v121, s[52:53] offset:128
	s_add_u32 s52, s52, 20480
	s_addc_u32 s53, s53, 0
	global_store_dword v122, v134, s[52:53]
	global_store_dword v122, v135, s[52:53] offset:128
	s_add_u32 s52, s52, 4096
	s_addc_u32 s53, s53, 0
	global_store_dword v122, v136, s[52:53]
	global_store_dword v122, v137, s[52:53] offset:128
	s_add_u32 s52, s52, 4096
	s_addc_u32 s53, s53, 0
	global_store_dword v122, v138, s[52:53]
	global_store_dword v122, v139, s[52:53] offset:128
	s_add_u32 s52, s52, 4096
	s_addc_u32 s53, s53, 0
	global_store_dword v122, v140, s[52:53]
	global_store_dword v122, v141, s[52:53] offset:128
	s_add_u32 s52, s80, 131072
	s_addc_u32 s53, s81, 0
	global_load_dword v114, v122, s[52:53]
	global_load_dword v115, v122, s[52:53] offset:128
	s_add_u32 s52, s52, 4096
	s_addc_u32 s53, s53, 0
	global_load_dword v116, v122, s[52:53]
	global_load_dword v117, v122, s[52:53] offset:128
	s_add_u32 s52, s52, 4096
	s_addc_u32 s53, s53, 0
	global_load_dword v118, v122, s[52:53]
	global_load_dword v119, v122, s[52:53] offset:128
	s_add_u32 s52, s52, 4096
	s_addc_u32 s53, s53, 0
	global_load_dword v120, v122, s[52:53]
	global_load_dword v121, v122, s[52:53] offset:128
	s_add_u32 s52, s52, 20480
	s_addc_u32 s53, s53, 0
	global_load_dword v134, v122, s[52:53]
	global_load_dword v135, v122, s[52:53] offset:128
	s_add_u32 s52, s52, 4096
	s_addc_u32 s53, s53, 0
	global_load_dword v136, v122, s[52:53]
	global_load_dword v137, v122, s[52:53] offset:128
	s_add_u32 s52, s52, 4096
	s_addc_u32 s53, s53, 0
	global_load_dword v138, v122, s[52:53]
	global_load_dword v139, v122, s[52:53] offset:128
	s_add_u32 s52, s52, 4096
	s_addc_u32 s53, s53, 0
	global_load_dword v140, v122, s[52:53]
	global_load_dword v141, v122, s[52:53] offset:128
	s_waitcnt vmcnt(0)
	v_fmac_f32_e32 v114, v34, v124
	v_fmac_f32_e32 v115, v50, v142
	v_fmac_f32_e32 v116, v35, v124
	v_fmac_f32_e32 v117, v51, v142
	v_fmac_f32_e32 v118, v36, v124
	v_fmac_f32_e32 v119, v52, v142
	v_fmac_f32_e32 v120, v37, v124
	v_fmac_f32_e32 v121, v53, v142
	v_fmac_f32_e32 v134, v38, v124
	v_fmac_f32_e32 v135, v54, v142
	v_fmac_f32_e32 v136, v39, v124
	v_fmac_f32_e32 v137, v55, v142
	v_fmac_f32_e32 v138, v40, v124
	v_fmac_f32_e32 v139, v56, v142
	v_fmac_f32_e32 v140, v41, v124
	v_fmac_f32_e32 v141, v57, v142
	s_add_u32 s52, s80, 131072
	s_addc_u32 s53, s81, 0
	global_store_dword v122, v114, s[52:53]
	global_store_dword v122, v115, s[52:53] offset:128
	s_add_u32 s52, s52, 4096
	s_addc_u32 s53, s53, 0
	global_store_dword v122, v116, s[52:53]
	global_store_dword v122, v117, s[52:53] offset:128
	s_add_u32 s52, s52, 4096
	s_addc_u32 s53, s53, 0
	global_store_dword v122, v118, s[52:53]
	global_store_dword v122, v119, s[52:53] offset:128
	s_add_u32 s52, s52, 4096
	s_addc_u32 s53, s53, 0
	global_store_dword v122, v120, s[52:53]
	global_store_dword v122, v121, s[52:53] offset:128
	s_add_u32 s52, s52, 20480
	s_addc_u32 s53, s53, 0
	global_store_dword v122, v134, s[52:53]
	global_store_dword v122, v135, s[52:53] offset:128
	s_add_u32 s52, s52, 4096
	s_addc_u32 s53, s53, 0
	global_store_dword v122, v136, s[52:53]
	global_store_dword v122, v137, s[52:53] offset:128
	s_add_u32 s52, s52, 4096
	s_addc_u32 s53, s53, 0
	global_store_dword v122, v138, s[52:53]
	global_store_dword v122, v139, s[52:53] offset:128
	s_add_u32 s52, s52, 4096
	s_addc_u32 s53, s53, 0
	global_store_dword v122, v140, s[52:53]
	global_store_dword v122, v141, s[52:53] offset:128
	s_add_u32 s52, s80, 196608
	s_addc_u32 s53, s81, 0
	global_load_dword v114, v122, s[52:53]
	global_load_dword v115, v122, s[52:53] offset:128
	s_add_u32 s52, s52, 4096
	s_addc_u32 s53, s53, 0
	global_load_dword v116, v122, s[52:53]
	global_load_dword v117, v122, s[52:53] offset:128
	s_add_u32 s52, s52, 4096
	s_addc_u32 s53, s53, 0
	global_load_dword v118, v122, s[52:53]
	global_load_dword v119, v122, s[52:53] offset:128
	s_add_u32 s52, s52, 4096
	s_addc_u32 s53, s53, 0
	global_load_dword v120, v122, s[52:53]
	global_load_dword v121, v122, s[52:53] offset:128
	s_add_u32 s52, s52, 20480
	s_addc_u32 s53, s53, 0
	global_load_dword v134, v122, s[52:53]
	global_load_dword v135, v122, s[52:53] offset:128
	s_add_u32 s52, s52, 4096
	s_addc_u32 s53, s53, 0
	global_load_dword v136, v122, s[52:53]
	global_load_dword v137, v122, s[52:53] offset:128
	s_add_u32 s52, s52, 4096
	s_addc_u32 s53, s53, 0
	global_load_dword v138, v122, s[52:53]
	global_load_dword v139, v122, s[52:53] offset:128
	s_add_u32 s52, s52, 4096
	s_addc_u32 s53, s53, 0
	global_load_dword v140, v122, s[52:53]
	global_load_dword v141, v122, s[52:53] offset:128
	s_waitcnt vmcnt(0)
; template <int AI, int BI>
; DI void dn_tile(const Params& p, char* wsb, int layer, int sub, bool final_out, int m0, int n0, char* lds) {
;     ...
; #pragma unroll
;   for (int bi = 0; bi < BI; ++bi) {
;     const int n = n0 + wb * 32 * BI + bi * 32 + r;
;     const float gv = 0.5f * gate[n];
;     const unsigned ib = (unsigned)((m0e + wa * 32 * AI + 4 * h) * 1024 + n);
; #pragma unroll
;     for (int ai = 0; ai < AI; ++ai)
; #pragma unroll
;       for (int reg = 0; reg < 16; ++reg) {
;         const unsigned idx = ib + (unsigned)((ai * 32 + (reg & 3) + 8 * (reg >> 2)) * 1024);
;         float v = xsu[idx] + gv * acc[ai][bi][reg];
;         if (final_out) outu[idx] = v; else xsu[idx] = v;
;         if ((reg & 7) == 7) __builtin_amdgcn_sched_barrier(0);
;       }
;   }
	v_fmac_f32_e32 v114, v42, v124
	v_fmac_f32_e32 v115, v58, v142
	v_fmac_f32_e32 v116, v43, v124
	v_fmac_f32_e32 v117, v59, v142
	v_fmac_f32_e32 v118, v44, v124
	v_fmac_f32_e32 v119, v60, v142
	v_fmac_f32_e32 v120, v45, v124
	v_fmac_f32_e32 v121, v61, v142
	v_fmac_f32_e32 v134, v46, v124
	v_fmac_f32_e32 v135, v62, v142
	v_fmac_f32_e32 v136, v47, v124
	v_fmac_f32_e32 v137, v63, v142
	v_fmac_f32_e32 v138, v48, v124
	v_fmac_f32_e32 v139, v64, v142
	v_fmac_f32_e32 v140, v49, v124
	v_fmac_f32_e32 v141, v65, v142
	s_add_u32 s52, s80, 196608
	s_addc_u32 s53, s81, 0
	global_store_dword v122, v114, s[52:53]
	global_store_dword v122, v115, s[52:53] offset:128
	s_add_u32 s52, s52, 4096
	s_addc_u32 s53, s53, 0
	global_store_dword v122, v116, s[52:53]
	global_store_dword v122, v117, s[52:53] offset:128
	s_add_u32 s52, s52, 4096
	s_addc_u32 s53, s53, 0
	global_store_dword v122, v118, s[52:53]
	global_store_dword v122, v119, s[52:53] offset:128
	s_add_u32 s52, s52, 4096
	s_addc_u32 s53, s53, 0
	global_store_dword v122, v120, s[52:53]
	global_store_dword v122, v121, s[52:53] offset:128
	s_add_u32 s52, s52, 20480
	s_addc_u32 s53, s53, 0
	global_store_dword v122, v134, s[52:53]
	global_store_dword v122, v135, s[52:53] offset:128
	s_add_u32 s52, s52, 4096
	s_addc_u32 s53, s53, 0
	global_store_dword v122, v136, s[52:53]
	global_store_dword v122, v137, s[52:53] offset:128
	s_add_u32 s52, s52, 4096
	s_addc_u32 s53, s53, 0
	global_store_dword v122, v138, s[52:53]
	global_store_dword v122, v139, s[52:53] offset:128
	s_add_u32 s52, s52, 4096
	s_addc_u32 s53, s53, 0
	global_store_dword v122, v140, s[52:53]
	global_store_dword v122, v141, s[52:53] offset:128
	s_add_u32 s80, s80, 0x80000
	s_addc_u32 s81, s81, 0
	s_add_u32 s52, s80, 0
	s_addc_u32 s53, s81, 0
	global_load_dword v114, v122, s[52:53]
	global_load_dword v115, v122, s[52:53] offset:128
	s_add_u32 s52, s52, 4096
	s_addc_u32 s53, s53, 0
	global_load_dword v116, v122, s[52:53]
	global_load_dword v117, v122, s[52:53] offset:128
	s_add_u32 s52, s52, 4096
	s_addc_u32 s53, s53, 0
	global_load_dword v118, v122, s[52:53]
	global_load_dword v119, v122, s[52:53] offset:128
	s_add_u32 s52, s52, 4096
	s_addc_u32 s53, s53, 0
	global_load_dword v120, v122, s[52:53]
	global_load_dword v121, v122, s[52:53] offset:128
	s_add_u32 s52, s52, 20480
	s_addc_u32 s53, s53, 0
	global_load_dword v134, v122, s[52:53]
	global_load_dword v135, v122, s[52:53] offset:128
	s_add_u32 s52, s52, 4096
	s_addc_u32 s53, s53, 0
	global_load_dword v136, v122, s[52:53]
	global_load_dword v137, v122, s[52:53] offset:128
	s_add_u32 s52, s52, 4096
	s_addc_u32 s53, s53, 0
	global_load_dword v138, v122, s[52:53]
	global_load_dword v139, v122, s[52:53] offset:128
	s_add_u32 s52, s52, 4096
	s_addc_u32 s53, s53, 0
	global_load_dword v140, v122, s[52:53]
	global_load_dword v141, v122, s[52:53] offset:128
	s_waitcnt vmcnt(0)
	v_fmac_f32_e32 v114, v66, v124
	v_fmac_f32_e32 v115, v82, v142
	v_fmac_f32_e32 v116, v67, v124
	v_fmac_f32_e32 v117, v83, v142
	v_fmac_f32_e32 v118, v68, v124
	v_fmac_f32_e32 v119, v84, v142
	v_fmac_f32_e32 v120, v69, v124
	v_fmac_f32_e32 v121, v85, v142
	v_fmac_f32_e32 v134, v70, v124
	v_fmac_f32_e32 v135, v86, v142
	v_fmac_f32_e32 v136, v71, v124
	v_fmac_f32_e32 v137, v87, v142
	v_fmac_f32_e32 v138, v72, v124
	v_fmac_f32_e32 v139, v88, v142
	v_fmac_f32_e32 v140, v73, v124
	v_fmac_f32_e32 v141, v89, v142
	s_add_u32 s52, s80, 0
	s_addc_u32 s53, s81, 0
	global_store_dword v122, v114, s[52:53]
	global_store_dword v122, v115, s[52:53] offset:128
	s_add_u32 s52, s52, 4096
	s_addc_u32 s53, s53, 0
	global_store_dword v122, v116, s[52:53]
	global_store_dword v122, v117, s[52:53] offset:128
	s_add_u32 s52, s52, 4096
	s_addc_u32 s53, s53, 0
	global_store_dword v122, v118, s[52:53]
	global_store_dword v122, v119, s[52:53] offset:128
	s_add_u32 s52, s52, 4096
	s_addc_u32 s53, s53, 0
	global_store_dword v122, v120, s[52:53]
	global_store_dword v122, v121, s[52:53] offset:128
	s_add_u32 s52, s52, 20480
	s_addc_u32 s53, s53, 0
	global_store_dword v122, v134, s[52:53]
	global_store_dword v122, v135, s[52:53] offset:128
	s_add_u32 s52, s52, 4096
	s_addc_u32 s53, s53, 0
	global_store_dword v122, v136, s[52:53]
	global_store_dword v122, v137, s[52:53] offset:128
	s_add_u32 s52, s52, 4096
	s_addc_u32 s53, s53, 0
	global_store_dword v122, v138, s[52:53]
	global_store_dword v122, v139, s[52:53] offset:128
	s_add_u32 s52, s52, 4096
	s_addc_u32 s53, s53, 0
	global_store_dword v122, v140, s[52:53]
	global_store_dword v122, v141, s[52:53] offset:128
	s_add_u32 s52, s80, 65536
	s_addc_u32 s53, s81, 0
	global_load_dword v114, v122, s[52:53]
	global_load_dword v115, v122, s[52:53] offset:128
	s_add_u32 s52, s52, 4096
	s_addc_u32 s53, s53, 0
	global_load_dword v116, v122, s[52:53]
	global_load_dword v117, v122, s[52:53] offset:128
	s_add_u32 s52, s52, 4096
	s_addc_u32 s53, s53, 0
	global_load_dword v118, v122, s[52:53]
	global_load_dword v119, v122, s[52:53] offset:128
	s_add_u32 s52, s52, 4096
	s_addc_u32 s53, s53, 0
	global_load_dword v120, v122, s[52:53]
	global_load_dword v121, v122, s[52:53] offset:128
	s_add_u32 s52, s52, 20480
	s_addc_u32 s53, s53, 0
	global_load_dword v134, v122, s[52:53]
	global_load_dword v135, v122, s[52:53] offset:128
	s_add_u32 s52, s52, 4096
	s_addc_u32 s53, s53, 0
	global_load_dword v136, v122, s[52:53]
	global_load_dword v137, v122, s[52:53] offset:128
	s_add_u32 s52, s52, 4096
	s_addc_u32 s53, s53, 0
	global_load_dword v138, v122, s[52:53]
	global_load_dword v139, v122, s[52:53] offset:128
	s_add_u32 s52, s52, 4096
	s_addc_u32 s53, s53, 0
	global_load_dword v140, v122, s[52:53]
	global_load_dword v141, v122, s[52:53] offset:128
	s_waitcnt vmcnt(0)
; template <int AI, int BI>
; DI void dn_tile(const Params& p, char* wsb, int layer, int sub, bool final_out, int m0, int n0, char* lds) {
;     ...
; #pragma unroll
;   for (int bi = 0; bi < BI; ++bi) {
;     const int n = n0 + wb * 32 * BI + bi * 32 + r;
;     const float gv = 0.5f * gate[n];
;     const unsigned ib = (unsigned)((m0e + wa * 32 * AI + 4 * h) * 1024 + n);
; #pragma unroll
;     for (int ai = 0; ai < AI; ++ai)
; #pragma unroll
;       for (int reg = 0; reg < 16; ++reg) {
;         const unsigned idx = ib + (unsigned)((ai * 32 + (reg & 3) + 8 * (reg >> 2)) * 1024);
;         float v = xsu[idx] + gv * acc[ai][bi][reg];
;         if (final_out) outu[idx] = v; else xsu[idx] = v;
;         if ((reg & 7) == 7) __builtin_amdgcn_sched_barrier(0);
;       }
;   }
	v_fmac_f32_e32 v114, v74, v124
	v_fmac_f32_e32 v115, v90, v142
	v_fmac_f32_e32 v116, v75, v124
	v_fmac_f32_e32 v117, v91, v142
	v_fmac_f32_e32 v118, v76, v124
	v_fmac_f32_e32 v119, v92, v142
	v_fmac_f32_e32 v120, v77, v124
	v_fmac_f32_e32 v121, v93, v142
	v_fmac_f32_e32 v134, v78, v124
	v_fmac_f32_e32 v135, v94, v142
	v_fmac_f32_e32 v136, v79, v124
	v_fmac_f32_e32 v137, v95, v142
	v_fmac_f32_e32 v138, v80, v124
	v_fmac_f32_e32 v139, v96, v142
	v_fmac_f32_e32 v140, v81, v124
	v_fmac_f32_e32 v141, v97, v142
	s_add_u32 s52, s80, 65536
	s_addc_u32 s53, s81, 0
	global_store_dword v122, v114, s[52:53]
	global_store_dword v122, v115, s[52:53] offset:128
	s_add_u32 s52, s52, 4096
	s_addc_u32 s53, s53, 0
	global_store_dword v122, v116, s[52:53]
	global_store_dword v122, v117, s[52:53] offset:128
	s_add_u32 s52, s52, 4096
	s_addc_u32 s53, s53, 0
	global_store_dword v122, v118, s[52:53]
	global_store_dword v122, v119, s[52:53] offset:128
	s_add_u32 s52, s52, 4096
	s_addc_u32 s53, s53, 0
	global_store_dword v122, v120, s[52:53]
	global_store_dword v122, v121, s[52:53] offset:128
	s_add_u32 s52, s52, 20480
	s_addc_u32 s53, s53, 0
	global_store_dword v122, v134, s[52:53]
	global_store_dword v122, v135, s[52:53] offset:128
	s_add_u32 s52, s52, 4096
	s_addc_u32 s53, s53, 0
	global_store_dword v122, v136, s[52:53]
	global_store_dword v122, v137, s[52:53] offset:128
	s_add_u32 s52, s52, 4096
	s_addc_u32 s53, s53, 0
	global_store_dword v122, v138, s[52:53]
	global_store_dword v122, v139, s[52:53] offset:128
	s_add_u32 s52, s52, 4096
	s_addc_u32 s53, s53, 0
	global_store_dword v122, v140, s[52:53]
	global_store_dword v122, v141, s[52:53] offset:128
	s_add_u32 s52, s80, 131072
	s_addc_u32 s53, s81, 0
	global_load_dword v114, v122, s[52:53]
	global_load_dword v115, v122, s[52:53] offset:128
	s_add_u32 s52, s52, 4096
	s_addc_u32 s53, s53, 0
	global_load_dword v116, v122, s[52:53]
	global_load_dword v117, v122, s[52:53] offset:128
	s_add_u32 s52, s52, 4096
	s_addc_u32 s53, s53, 0
	global_load_dword v118, v122, s[52:53]
	global_load_dword v119, v122, s[52:53] offset:128
	s_add_u32 s52, s52, 4096
	s_addc_u32 s53, s53, 0
	global_load_dword v120, v122, s[52:53]
	global_load_dword v121, v122, s[52:53] offset:128
	s_add_u32 s52, s52, 20480
	s_addc_u32 s53, s53, 0
	global_load_dword v134, v122, s[52:53]
	global_load_dword v135, v122, s[52:53] offset:128
	s_add_u32 s52, s52, 4096
	s_addc_u32 s53, s53, 0
	global_load_dword v136, v122, s[52:53]
	global_load_dword v137, v122, s[52:53] offset:128
	s_add_u32 s52, s52, 4096
	s_addc_u32 s53, s53, 0
	global_load_dword v138, v122, s[52:53]
	global_load_dword v139, v122, s[52:53] offset:128
	s_add_u32 s52, s52, 4096
	s_addc_u32 s53, s53, 0
	global_load_dword v140, v122, s[52:53]
	global_load_dword v141, v122, s[52:53] offset:128
	s_waitcnt vmcnt(0)
; template <int AI, int BI>
; DI void dn_tile(const Params& p, char* wsb, int layer, int sub, bool final_out, int m0, int n0, char* lds) {
;     ...
; #pragma unroll
;   for (int bi = 0; bi < BI; ++bi) {
;     const int n = n0 + wb * 32 * BI + bi * 32 + r;
;     const float gv = 0.5f * gate[n];
;     const unsigned ib = (unsigned)((m0e + wa * 32 * AI + 4 * h) * 1024 + n);
; #pragma unroll
;     for (int ai = 0; ai < AI; ++ai)
; #pragma unroll
;       for (int reg = 0; reg < 16; ++reg) {
;         const unsigned idx = ib + (unsigned)((ai * 32 + (reg & 3) + 8 * (reg >> 2)) * 1024);
;         float v = xsu[idx] + gv * acc[ai][bi][reg];
;         if (final_out) outu[idx] = v; else xsu[idx] = v;
;         if ((reg & 7) == 7) __builtin_amdgcn_sched_barrier(0);
;       }
;   }
	v_fmac_f32_e32 v114, v98, v124
	v_fmac_f32_e32 v115, v214, v142
	v_fmac_f32_e32 v116, v99, v124
	v_fmac_f32_e32 v117, v215, v142
	v_fmac_f32_e32 v118, v100, v124
	v_fmac_f32_e32 v119, v216, v142
	v_fmac_f32_e32 v120, v101, v124
	v_fmac_f32_e32 v121, v217, v142
	v_fmac_f32_e32 v134, v102, v124
	v_fmac_f32_e32 v135, v218, v142
	v_fmac_f32_e32 v136, v103, v124
	v_fmac_f32_e32 v137, v219, v142
	v_fmac_f32_e32 v138, v104, v124
	v_fmac_f32_e32 v139, v220, v142
	v_fmac_f32_e32 v140, v105, v124
	v_fmac_f32_e32 v141, v221, v142
	s_add_u32 s52, s80, 131072
	s_addc_u32 s53, s81, 0
	global_store_dword v122, v114, s[52:53]
	global_store_dword v122, v115, s[52:53] offset:128
	s_add_u32 s52, s52, 4096
	s_addc_u32 s53, s53, 0
	global_store_dword v122, v116, s[52:53]
	global_store_dword v122, v117, s[52:53] offset:128
	s_add_u32 s52, s52, 4096
	s_addc_u32 s53, s53, 0
	global_store_dword v122, v118, s[52:53]
	global_store_dword v122, v119, s[52:53] offset:128
	s_add_u32 s52, s52, 4096
	s_addc_u32 s53, s53, 0
	global_store_dword v122, v120, s[52:53]
	global_store_dword v122, v121, s[52:53] offset:128
	s_add_u32 s52, s52, 20480
	s_addc_u32 s53, s53, 0
	global_store_dword v122, v134, s[52:53]
	global_store_dword v122, v135, s[52:53] offset:128
	s_add_u32 s52, s52, 4096
	s_addc_u32 s53, s53, 0
	global_store_dword v122, v136, s[52:53]
	global_store_dword v122, v137, s[52:53] offset:128
	s_add_u32 s52, s52, 4096
	s_addc_u32 s53, s53, 0
	global_store_dword v122, v138, s[52:53]
	global_store_dword v122, v139, s[52:53] offset:128
	s_add_u32 s52, s52, 4096
	s_addc_u32 s53, s53, 0
	global_store_dword v122, v140, s[52:53]
	global_store_dword v122, v141, s[52:53] offset:128
	s_add_u32 s52, s80, 196608
	s_addc_u32 s53, s81, 0
	global_load_dword v114, v122, s[52:53]
	global_load_dword v115, v122, s[52:53] offset:128
	s_add_u32 s52, s52, 4096
	s_addc_u32 s53, s53, 0
	global_load_dword v116, v122, s[52:53]
	global_load_dword v117, v122, s[52:53] offset:128
	s_add_u32 s52, s52, 4096
	s_addc_u32 s53, s53, 0
	global_load_dword v118, v122, s[52:53]
	global_load_dword v119, v122, s[52:53] offset:128
	s_add_u32 s52, s52, 4096
	s_addc_u32 s53, s53, 0
	global_load_dword v120, v122, s[52:53]
	global_load_dword v121, v122, s[52:53] offset:128
	s_add_u32 s52, s52, 20480
	s_addc_u32 s53, s53, 0
	global_load_dword v134, v122, s[52:53]
	global_load_dword v135, v122, s[52:53] offset:128
	s_add_u32 s52, s52, 4096
	s_addc_u32 s53, s53, 0
	global_load_dword v136, v122, s[52:53]
	global_load_dword v137, v122, s[52:53] offset:128
	s_add_u32 s52, s52, 4096
	s_addc_u32 s53, s53, 0
	global_load_dword v138, v122, s[52:53]
	global_load_dword v139, v122, s[52:53] offset:128
	s_add_u32 s52, s52, 4096
	s_addc_u32 s53, s53, 0
	global_load_dword v140, v122, s[52:53]
	global_load_dword v141, v122, s[52:53] offset:128
	s_waitcnt vmcnt(0)
	v_fmac_f32_e32 v114, v106, v124
	v_fmac_f32_e32 v115, v222, v142
	v_fmac_f32_e32 v116, v107, v124
	v_fmac_f32_e32 v117, v223, v142
	v_fmac_f32_e32 v118, v108, v124
	v_fmac_f32_e32 v119, v224, v142
	v_fmac_f32_e32 v120, v109, v124
	v_fmac_f32_e32 v121, v225, v142
	v_fmac_f32_e32 v134, v110, v124
	v_fmac_f32_e32 v135, v226, v142
	v_fmac_f32_e32 v136, v111, v124
	v_fmac_f32_e32 v137, v227, v142
	v_fmac_f32_e32 v138, v112, v124
	v_fmac_f32_e32 v139, v228, v142
	v_fmac_f32_e32 v140, v113, v124
	v_fmac_f32_e32 v141, v229, v142
	s_add_u32 s52, s80, 196608
	s_addc_u32 s53, s81, 0
	global_store_dword v122, v114, s[52:53]
	global_store_dword v122, v115, s[52:53] offset:128
	s_add_u32 s52, s52, 4096
	s_addc_u32 s53, s53, 0
	global_store_dword v122, v116, s[52:53]
	global_store_dword v122, v117, s[52:53] offset:128
	s_add_u32 s52, s52, 4096
	s_addc_u32 s53, s53, 0
	global_store_dword v122, v118, s[52:53]
	global_store_dword v122, v119, s[52:53] offset:128
	s_add_u32 s52, s52, 4096
	s_addc_u32 s53, s53, 0
	global_store_dword v122, v120, s[52:53]
	global_store_dword v122, v121, s[52:53] offset:128
	s_add_u32 s52, s52, 20480
	s_addc_u32 s53, s53, 0
	global_store_dword v122, v134, s[52:53]
	global_store_dword v122, v135, s[52:53] offset:128
	s_add_u32 s52, s52, 4096
	s_addc_u32 s53, s53, 0
	global_store_dword v122, v136, s[52:53]
	global_store_dword v122, v137, s[52:53] offset:128
	s_add_u32 s52, s52, 4096
	s_addc_u32 s53, s53, 0
	global_store_dword v122, v138, s[52:53]
	global_store_dword v122, v139, s[52:53] offset:128
	s_add_u32 s52, s52, 4096
	s_addc_u32 s53, s53, 0
	global_store_dword v122, v140, s[52:53]
	global_store_dword v122, v141, s[52:53] offset:128
	s_branch .LBB0_478

; #define TIDX opaque_tid()
; template <int AI, int BI>
; DI void gemm_stage(const u16* __restrict__ A, int lda, const u16* __restrict__ B, int ldb, char* buf, int tid) {
; #pragma unroll
;   for (int i = 0; i < 2 * AI; ++i) {
;     const int S = tid + NTHR * i, row = S >> 3, c = (S & 7) ^ ((row >> 1) & 7);
;     __builtin_amdgcn_global_load_lds((const unsigned*)(A + (size_t)row * lda + c * 8), (__attribute__((address_space(3))) unsigned*)(buf + S * 16), 16, 0, 0);
;   }
; #pragma unroll
;   for (int i = 0; i < 2 * BI; ++i) {
;     const int S = tid + NTHR * i, row = S >> 3, c = (S & 7) ^ ((row >> 1) & 7);
;     __builtin_amdgcn_global_load_lds((const unsigned*)(B + (size_t)row * ldb + c * 8), (__attribute__((address_space(3))) unsigned*)(buf + 16384 + S * 16), 16, 0, 0);
;   }
; }
; template <int AI, int BI>
; DI void gemm_tile(const u16* __restrict__ A, int lda, const u16* __restrict__ B, int ldb, int nk, bool swap,
;                   f32x16 (&acc)[AI][BI], char* lds) {
;   const int tid = TIDX, lane = tid & 63, wid = tid >> 6;
;   gemm_stage<AI, BI>(A, lda, B, ldb, lds, tid);
;   asm volatile("s_waitcnt vmcnt(0)" ::: "memory");
;   __syncthreads();
;   const int wa = wid >> 1, wb = wid & 1, r = lane & 31, h = lane >> 5, sw = (r >> 1) & 7;
;   const int offA = (swap ? 16384 : 0) + (wa * 32 * AI + r) * 128;
;   const int offB = (swap ? 0 : 16384) + (wb * 32 * BI + r) * 128;
;   for (int kt = 0; kt < nk; ++kt) {
;     const char* cur = lds + (kt & 1) * 32768;
;     if (kt + 1 < nk) gemm_stage<AI, BI>(A + (kt + 1) * 64, lda, B + (kt + 1) * 64, ldb, lds + ((kt + 1) & 1) * 32768, tid);
; #pragma unroll
;     for (int ks = 0; ks < 4; ++ks) {
;       const int co = ((ks * 2 + h) ^ sw) << 4;
;       s16x8 fa[AI], fb[BI];
; #pragma unroll
;       for (int i = 0; i < AI; ++i) fa[i] = *(const s16x8*)(cur + offA + i * 4096 + co);
; #pragma unroll
;       for (int i = 0; i < BI; ++i) fb[i] = *(const s16x8*)(cur + offB + i * 4096 + co);
; #pragma unroll
;       for (int i = 0; i < AI; ++i)
; #pragma unroll
;         for (int j = 0; j < BI; ++j) acc[i][j] = MFMA(fa[i], fb[j], acc[i][j]);
;     }
; DI void phase_dn(const Params& p, char* wsb, int layer, int sub, int mrows, bool final_out, char* lds) {
;   int mt, nt;
;   for (int rnd = 0; next_tile(rnd, 128, 8, mt, nt); ++rnd) dn_tile<2, 2>(p, wsb, layer, sub, final_out, mt * 128, nt * 128, lds);
.LBB0_1260:
	s_or_b64 exec, exec, s[6:7]
	s_mov_b64 s[8:9], s[20:21]
	s_mov_b32 s29, s19
	s_mov_b64 s[14:15], s[26:27]
	s_waitcnt lgkmcnt(0)
	s_barrier
	s_add_u32 s6, s14, s29
	s_addc_u32 s7, s15, 0
	s_add_u32 s16, s6, 0x9bb7000
	s_addc_u32 s17, s7, 0
	s_add_u32 s18, s6, 0x1e037000
	s_addc_u32 s28, s7, 0
	s_mov_b64 s[10:11], s[22:23]
	s_add_u32 s8, s6, 0x2fb7000
	s_addc_u32 s9, s7, 0
	v_readlane_b32 s10, v242, 2
	s_add_u32 s34, s6, s10
	s_addc_u32 s35, s7, 0
	v_readlane_b32 s6, v242, 7
	v_readlane_b32 s7, v242, 8
	s_and_b64 vcc, exec, s[6:7]
	s_mov_b64 s[12:13], s[24:25]
	s_cbranch_vccnz .LBB0_1521
	v_readlane_b32 s6, v243, 12
	s_add_u32 s36, s6, s29
	v_readlane_b32 s6, v243, 13
	s_addc_u32 s37, s6, 0
	v_readlane_b32 s6, v243, 27
	s_add_u32 s10, s6, s29
	v_readlane_b32 s6, v243, 28
	s_addc_u32 s11, s6, 0
	v_readlane_b32 s40, v243, 18
	s_cmpk_lg_u32 s92, 0x200
	s_cbranch_scc1 .LBB0_1263
	v_and_b32_e32 v0, 31, v178
	v_bfe_u32 v122, v178, 5, 1
	v_bfe_u32 v123, v178, 2, 2
	v_xor_b32_e32 v122, v122, v123
	v_lshlrev_b32_e32 v122, 4, v122
	v_bfe_u32 v123, v178, 7, 1
	v_lshl_add_u32 v123, v123, 6, v0
	v_lshl_add_u32 v142, v123, 6, v122
	v_xor_b32_e32 v143, 32, v142
	v_bfe_u32 v123, v178, 6, 1
	v_lshl_add_u32 v123, v123, 6, v0
	v_lshl_add_u32 v144, v123, 6, v122
	v_add_u32_e32 v144, 0xc000, v144
	v_xor_b32_e32 v145, 32, v144
	v_lshrrev_b32_e32 v0, 2, v178
	v_bfe_u32 v122, v178, 4, 2
	v_and_b32_e32 v123, 3, v178
	v_xor_b32_e32 v122, v122, v123
	v_lshlrev_b32_e32 v122, 4, v122
	v_mul_u32_u24_e32 v0, 0x1600, v0
	v_add_u32_e32 v126, v0, v122
	v_add_u32_e32 v127, 0x58000, v126
	v_add_u32_e32 v128, 0xb0000, v126
	v_add_u32_e32 v129, 0x108000, v126
	v_lshrrev_b32_e32 v0, 6, v178
	s_nop 1
	v_readfirstlane_b32 s68, v0
	s_lshl_b32 s68, s68, 10
	s_and_b32 s71, s96, 7
	s_lshr_b32 s70, s96, 3
	s_and_b32 s72, s70, 7
	s_lshl_b32 s74, s71, 3
	s_add_u32 s72, s72, s74
	s_lshr_b32 s73, s70, 3
	s_mul_i32 s74, s72, 0x160000
	s_add_u32 s64, s16, s74
	s_addc_u32 s65, s17, 0
	s_mul_i32 s74, s73, 0xb0000
	s_add_u32 s66, s18, s74
	s_addc_u32 s67, s28, 0
	s_add_u32 m0, s68, 0
	s_nop 0
	global_load_lds_dwordx4 v126, s[64:65]
	s_add_u32 m0, s68, 4096
	s_nop 0
	global_load_lds_dwordx4 v127, s[64:65]
	s_add_u32 m0, s68, 8192
	s_nop 0
	global_load_lds_dwordx4 v128, s[64:65]
	s_add_u32 m0, s68, 12288
	s_nop 0
	global_load_lds_dwordx4 v129, s[64:65]
	s_add_u32 m0, s68, 49152
	s_nop 0
	global_load_lds_dwordx4 v126, s[66:67]
	s_add_u32 m0, s68, 53248
	s_nop 0
	global_load_lds_dwordx4 v127, s[66:67]
	s_add_u32 s64, s64, 64
	s_addc_u32 s65, s65, 0
	s_add_u32 s66, s66, 64
	s_addc_u32 s67, s67, 0
	s_add_u32 m0, s68, 16384
	s_nop 0
	global_load_lds_dwordx4 v126, s[64:65]
	s_add_u32 m0, s68, 20480
	s_nop 0
	global_load_lds_dwordx4 v127, s[64:65]
	s_add_u32 m0, s68, 24576
	s_nop 0
	global_load_lds_dwordx4 v128, s[64:65]
	s_add_u32 m0, s68, 28672
	s_nop 0
	global_load_lds_dwordx4 v129, s[64:65]
	s_add_u32 m0, s68, 57344
	s_nop 0
	global_load_lds_dwordx4 v126, s[66:67]
	s_add_u32 m0, s68, 61440
	s_nop 0
	global_load_lds_dwordx4 v127, s[66:67]
	s_add_u32 s64, s64, 64
	s_addc_u32 s65, s65, 0
	s_add_u32 s66, s66, 64
	s_addc_u32 s67, s67, 0
	s_waitcnt vmcnt(6)
	s_barrier
	ds_read_b128 v[114:117], v142 offset:0
	ds_read_b128 v[230:233], v144 offset:0
	ds_read_b128 v[234:237], v144 offset:2048
	ds_read_b128 v[118:121], v142 offset:2048
	ds_read_b128 v[134:137], v142 offset:8192
	ds_read_b128 v[138:141], v142 offset:10240
	ds_read_b128 v[238:241], v145 offset:0
	ds_read_b128 v[246:249], v145 offset:2048
	s_add_u32 m0, s68, 32768
	s_nop 0
	global_load_lds_dwordx4 v126, s[64:65]
	s_add_u32 m0, s68, 36864
	s_nop 0
	global_load_lds_dwordx4 v127, s[64:65]
	s_add_u32 m0, s68, 40960
	s_nop 0
	global_load_lds_dwordx4 v128, s[64:65]
	s_add_u32 m0, s68, 45056
	s_nop 0
	global_load_lds_dwordx4 v129, s[64:65]
	s_add_u32 m0, s68, 65664
	s_nop 0
	global_load_lds_dwordx4 v126, s[66:67]
	s_add_u32 m0, s68, 69760
	s_nop 0
	global_load_lds_dwordx4 v127, s[66:67]
	s_add_u32 s64, s64, 64
	s_addc_u32 s65, s65, 0
	s_add_u32 s66, s66, 64
	s_addc_u32 s67, s67, 0
	s_waitcnt lgkmcnt(6)
	v_mfma_f32_32x32x16_bf16 v[2:17], v[114:117], v[230:233], 0
	s_waitcnt lgkmcnt(5)
	v_mfma_f32_32x32x16_bf16 v[18:33], v[114:117], v[234:237], 0
	ds_read_b128 v[114:117], v143 offset:0
	s_waitcnt lgkmcnt(5)
	v_mfma_f32_32x32x16_bf16 v[34:49], v[118:121], v[230:233], 0
	v_mfma_f32_32x32x16_bf16 v[50:65], v[118:121], v[234:237], 0
	ds_read_b128 v[118:121], v143 offset:2048
	s_waitcnt lgkmcnt(5)
	v_mfma_f32_32x32x16_bf16 v[66:81], v[134:137], v[230:233], 0
	v_mfma_f32_32x32x16_bf16 v[82:97], v[134:137], v[234:237], 0
	ds_read_b128 v[134:137], v143 offset:8192
	s_waitcnt lgkmcnt(5)
	v_mfma_f32_32x32x16_bf16 v[98:113], v[138:141], v[230:233], 0
	v_mfma_f32_32x32x16_bf16 v[214:229], v[138:141], v[234:237], 0
	ds_read_b128 v[138:141], v143 offset:10240
	s_waitcnt lgkmcnt(3)
	v_mfma_f32_32x32x16_bf16 v[2:17], v[114:117], v[238:241], v[2:17]
	v_mfma_f32_32x32x16_bf16 v[18:33], v[114:117], v[246:249], v[18:33]
	s_waitcnt lgkmcnt(2)
	v_mfma_f32_32x32x16_bf16 v[34:49], v[118:121], v[238:241], v[34:49]
	v_mfma_f32_32x32x16_bf16 v[50:65], v[118:121], v[246:249], v[50:65]
	s_waitcnt lgkmcnt(1)
	v_mfma_f32_32x32x16_bf16 v[66:81], v[134:137], v[238:241], v[66:81]
	v_mfma_f32_32x32x16_bf16 v[82:97], v[134:137], v[246:249], v[82:97]
	s_waitcnt lgkmcnt(0)
	v_mfma_f32_32x32x16_bf16 v[98:113], v[138:141], v[238:241], v[98:113]
	v_mfma_f32_32x32x16_bf16 v[214:229], v[138:141], v[246:249], v[214:229]
	s_waitcnt vmcnt(6)
	s_barrier
; #define MFMA(a, b, c) __builtin_amdgcn_mfma_f32_32x32x16_bf16((a), (b), (c), 0, 0, 0)
; template <int AI, int BI>
; DI void gemm_tile(const u16* __restrict__ A, int lda, const u16* __restrict__ B, int ldb, int nk, bool swap,
;                   f32x16 (&acc)[AI][BI], char* lds) {
;     ...
;   for (int kt = 0; kt < nk; ++kt) {
;     const char* cur = lds + (kt & 1) * 32768;
;     if (kt + 1 < nk) gemm_stage<AI, BI>(A + (kt + 1) * 64, lda, B + (kt + 1) * 64, ldb, lds + ((kt + 1) & 1) * 32768, tid);
; #pragma unroll
;     for (int ks = 0; ks < 4; ++ks) {
;       const int co = ((ks * 2 + h) ^ sw) << 4;
;       s16x8 fa[AI], fb[BI];
; #pragma unroll
;       for (int i = 0; i < AI; ++i) fa[i] = *(const s16x8*)(cur + offA + i * 4096 + co);
; #pragma unroll
;       for (int i = 0; i < BI; ++i) fb[i] = *(const s16x8*)(cur + offB + i * 4096 + co);
; #pragma unroll
;       for (int i = 0; i < AI; ++i)
; #pragma unroll
;         for (int j = 0; j < BI; ++j) acc[i][j] = MFMA(fa[i], fb[j], acc[i][j]);
;     }
	ds_read_b128 v[114:117], v142 offset:16384
	ds_read_b128 v[230:233], v144 offset:8192
	ds_read_b128 v[234:237], v144 offset:10240
	ds_read_b128 v[118:121], v142 offset:18432
	ds_read_b128 v[134:137], v142 offset:24576
	ds_read_b128 v[138:141], v142 offset:26624
	ds_read_b128 v[238:241], v145 offset:8192
	ds_read_b128 v[246:249], v145 offset:10240
	s_add_u32 m0, s68, 0
	s_nop 0
	global_load_lds_dwordx4 v126, s[64:65]
	s_add_u32 m0, s68, 4096
	s_nop 0
	global_load_lds_dwordx4 v127, s[64:65]
	s_add_u32 m0, s68, 8192
	s_nop 0
	global_load_lds_dwordx4 v128, s[64:65]
	s_add_u32 m0, s68, 12288
	s_nop 0
	global_load_lds_dwordx4 v129, s[64:65]
	s_add_u32 m0, s68, 49152
	s_nop 0
	global_load_lds_dwordx4 v126, s[66:67]
	s_add_u32 m0, s68, 53248
	s_nop 0
	global_load_lds_dwordx4 v127, s[66:67]
	s_add_u32 s64, s64, 64
	s_addc_u32 s65, s65, 0
	s_add_u32 s66, s66, 64
	s_addc_u32 s67, s67, 0
	s_waitcnt lgkmcnt(6)
	v_mfma_f32_32x32x16_bf16 v[2:17], v[114:117], v[230:233], v[2:17]
	s_waitcnt lgkmcnt(5)
	v_mfma_f32_32x32x16_bf16 v[18:33], v[114:117], v[234:237], v[18:33]
	ds_read_b128 v[114:117], v143 offset:16384
	s_waitcnt lgkmcnt(5)
	v_mfma_f32_32x32x16_bf16 v[34:49], v[118:121], v[230:233], v[34:49]
	v_mfma_f32_32x32x16_bf16 v[50:65], v[118:121], v[234:237], v[50:65]
	ds_read_b128 v[118:121], v143 offset:18432
	s_waitcnt lgkmcnt(5)
	v_mfma_f32_32x32x16_bf16 v[66:81], v[134:137], v[230:233], v[66:81]
	v_mfma_f32_32x32x16_bf16 v[82:97], v[134:137], v[234:237], v[82:97]
	ds_read_b128 v[134:137], v143 offset:24576
	s_waitcnt lgkmcnt(5)
	v_mfma_f32_32x32x16_bf16 v[98:113], v[138:141], v[230:233], v[98:113]
	v_mfma_f32_32x32x16_bf16 v[214:229], v[138:141], v[234:237], v[214:229]
	ds_read_b128 v[138:141], v143 offset:26624
	s_waitcnt lgkmcnt(3)
	v_mfma_f32_32x32x16_bf16 v[2:17], v[114:117], v[238:241], v[2:17]
	v_mfma_f32_32x32x16_bf16 v[18:33], v[114:117], v[246:249], v[18:33]
	s_waitcnt lgkmcnt(2)
	v_mfma_f32_32x32x16_bf16 v[34:49], v[118:121], v[238:241], v[34:49]
	v_mfma_f32_32x32x16_bf16 v[50:65], v[118:121], v[246:249], v[50:65]
	s_waitcnt lgkmcnt(1)
	v_mfma_f32_32x32x16_bf16 v[66:81], v[134:137], v[238:241], v[66:81]
	v_mfma_f32_32x32x16_bf16 v[82:97], v[134:137], v[246:249], v[82:97]
	s_waitcnt lgkmcnt(0)
	v_mfma_f32_32x32x16_bf16 v[98:113], v[138:141], v[238:241], v[98:113]
	v_mfma_f32_32x32x16_bf16 v[214:229], v[138:141], v[246:249], v[214:229]
	s_waitcnt vmcnt(6)
	s_barrier
	ds_read_b128 v[114:117], v142 offset:32768
	ds_read_b128 v[230:233], v144 offset:16512
	ds_read_b128 v[234:237], v144 offset:18560
	ds_read_b128 v[118:121], v142 offset:34816
	ds_read_b128 v[134:137], v142 offset:40960
	ds_read_b128 v[138:141], v142 offset:43008
	ds_read_b128 v[238:241], v145 offset:16512
	ds_read_b128 v[246:249], v145 offset:18560
	s_add_u32 m0, s68, 16384
	s_nop 0
	global_load_lds_dwordx4 v126, s[64:65]
	s_add_u32 m0, s68, 20480
	s_nop 0
	global_load_lds_dwordx4 v127, s[64:65]
	s_add_u32 m0, s68, 24576
	s_nop 0
	global_load_lds_dwordx4 v128, s[64:65]
	s_add_u32 m0, s68, 28672
	s_nop 0
	global_load_lds_dwordx4 v129, s[64:65]
	s_add_u32 m0, s68, 57344
	s_nop 0
	global_load_lds_dwordx4 v126, s[66:67]
	s_add_u32 m0, s68, 61440
	s_nop 0
	global_load_lds_dwordx4 v127, s[66:67]
	s_add_u32 s64, s64, 64
	s_addc_u32 s65, s65, 0
	s_add_u32 s66, s66, 64
	s_addc_u32 s67, s67, 0
	s_waitcnt lgkmcnt(6)
	v_mfma_f32_32x32x16_bf16 v[2:17], v[114:117], v[230:233], v[2:17]
	s_waitcnt lgkmcnt(5)
	v_mfma_f32_32x32x16_bf16 v[18:33], v[114:117], v[234:237], v[18:33]
	ds_read_b128 v[114:117], v143 offset:32768
	s_waitcnt lgkmcnt(5)
	v_mfma_f32_32x32x16_bf16 v[34:49], v[118:121], v[230:233], v[34:49]
	v_mfma_f32_32x32x16_bf16 v[50:65], v[118:121], v[234:237], v[50:65]
	ds_read_b128 v[118:121], v143 offset:34816
	s_waitcnt lgkmcnt(5)
	v_mfma_f32_32x32x16_bf16 v[66:81], v[134:137], v[230:233], v[66:81]
	v_mfma_f32_32x32x16_bf16 v[82:97], v[134:137], v[234:237], v[82:97]
	ds_read_b128 v[134:137], v143 offset:40960
	s_waitcnt lgkmcnt(5)
	v_mfma_f32_32x32x16_bf16 v[98:113], v[138:141], v[230:233], v[98:113]
	v_mfma_f32_32x32x16_bf16 v[214:229], v[138:141], v[234:237], v[214:229]
	ds_read_b128 v[138:141], v143 offset:43008
	s_waitcnt lgkmcnt(3)
	v_mfma_f32_32x32x16_bf16 v[2:17], v[114:117], v[238:241], v[2:17]
	v_mfma_f32_32x32x16_bf16 v[18:33], v[114:117], v[246:249], v[18:33]
	s_waitcnt lgkmcnt(2)
	v_mfma_f32_32x32x16_bf16 v[34:49], v[118:121], v[238:241], v[34:49]
	v_mfma_f32_32x32x16_bf16 v[50:65], v[118:121], v[246:249], v[50:65]
	s_waitcnt lgkmcnt(1)
	v_mfma_f32_32x32x16_bf16 v[66:81], v[134:137], v[238:241], v[66:81]
	v_mfma_f32_32x32x16_bf16 v[82:97], v[134:137], v[246:249], v[82:97]
	s_waitcnt lgkmcnt(0)
	v_mfma_f32_32x32x16_bf16 v[98:113], v[138:141], v[238:241], v[98:113]
	v_mfma_f32_32x32x16_bf16 v[214:229], v[138:141], v[246:249], v[214:229]
	s_mov_b32 s69, 27
; #define MFMA(a, b, c) __builtin_amdgcn_mfma_f32_32x32x16_bf16((a), (b), (c), 0, 0, 0)
; template <int AI, int BI>
; DI void gemm_tile(const u16* __restrict__ A, int lda, const u16* __restrict__ B, int ldb, int nk, bool swap,
;                   f32x16 (&acc)[AI][BI], char* lds) {
;     ...
;   for (int kt = 0; kt < nk; ++kt) {
;     const char* cur = lds + (kt & 1) * 32768;
;     if (kt + 1 < nk) gemm_stage<AI, BI>(A + (kt + 1) * 64, lda, B + (kt + 1) * 64, ldb, lds + ((kt + 1) & 1) * 32768, tid);
; #pragma unroll
;     for (int ks = 0; ks < 4; ++ks) {
;       const int co = ((ks * 2 + h) ^ sw) << 4;
;       s16x8 fa[AI], fb[BI];
; #pragma unroll
;       for (int i = 0; i < AI; ++i) fa[i] = *(const s16x8*)(cur + offA + i * 4096 + co);
; #pragma unroll
;       for (int i = 0; i < BI; ++i) fb[i] = *(const s16x8*)(cur + offB + i * 4096 + co);
; #pragma unroll
;       for (int i = 0; i < AI; ++i)
; #pragma unroll
;         for (int j = 0; j < BI; ++j) acc[i][j] = MFMA(fa[i], fb[j], acc[i][j]);
;     }
;     asm volatile("s_waitcnt vmcnt(0)" ::: "memory");
;     __syncthreads();
;   }
.Ldn2_kloop:
	s_waitcnt vmcnt(6)
	s_barrier
	ds_read_b128 v[114:117], v142 offset:0
	ds_read_b128 v[230:233], v144 offset:0
	ds_read_b128 v[234:237], v144 offset:2048
	ds_read_b128 v[118:121], v142 offset:2048
	ds_read_b128 v[134:137], v142 offset:8192
	ds_read_b128 v[138:141], v142 offset:10240
	ds_read_b128 v[238:241], v145 offset:0
	ds_read_b128 v[246:249], v145 offset:2048
	s_add_u32 m0, s68, 32768
	s_nop 0
	global_load_lds_dwordx4 v126, s[64:65]
	s_add_u32 m0, s68, 36864
	s_nop 0
	global_load_lds_dwordx4 v127, s[64:65]
	s_add_u32 m0, s68, 40960
	s_nop 0
	global_load_lds_dwordx4 v128, s[64:65]
	s_add_u32 m0, s68, 45056
	s_nop 0
	global_load_lds_dwordx4 v129, s[64:65]
	s_add_u32 m0, s68, 65664
	s_nop 0
	global_load_lds_dwordx4 v126, s[66:67]
	s_add_u32 m0, s68, 69760
	s_nop 0
	global_load_lds_dwordx4 v127, s[66:67]
	s_add_u32 s64, s64, 64
	s_addc_u32 s65, s65, 0
	s_add_u32 s66, s66, 64
	s_addc_u32 s67, s67, 0
	s_waitcnt lgkmcnt(6)
	v_mfma_f32_32x32x16_bf16 v[2:17], v[114:117], v[230:233], v[2:17]
	s_waitcnt lgkmcnt(5)
	v_mfma_f32_32x32x16_bf16 v[18:33], v[114:117], v[234:237], v[18:33]
	ds_read_b128 v[114:117], v143 offset:0
	s_waitcnt lgkmcnt(5)
	v_mfma_f32_32x32x16_bf16 v[34:49], v[118:121], v[230:233], v[34:49]
	v_mfma_f32_32x32x16_bf16 v[50:65], v[118:121], v[234:237], v[50:65]
	ds_read_b128 v[118:121], v143 offset:2048
	s_waitcnt lgkmcnt(5)
	v_mfma_f32_32x32x16_bf16 v[66:81], v[134:137], v[230:233], v[66:81]
	v_mfma_f32_32x32x16_bf16 v[82:97], v[134:137], v[234:237], v[82:97]
	ds_read_b128 v[134:137], v143 offset:8192
	s_waitcnt lgkmcnt(5)
	v_mfma_f32_32x32x16_bf16 v[98:113], v[138:141], v[230:233], v[98:113]
	v_mfma_f32_32x32x16_bf16 v[214:229], v[138:141], v[234:237], v[214:229]
	ds_read_b128 v[138:141], v143 offset:10240
	s_waitcnt lgkmcnt(3)
	v_mfma_f32_32x32x16_bf16 v[2:17], v[114:117], v[238:241], v[2:17]
	v_mfma_f32_32x32x16_bf16 v[18:33], v[114:117], v[246:249], v[18:33]
	s_waitcnt lgkmcnt(2)
	v_mfma_f32_32x32x16_bf16 v[34:49], v[118:121], v[238:241], v[34:49]
	v_mfma_f32_32x32x16_bf16 v[50:65], v[118:121], v[246:249], v[50:65]
	s_waitcnt lgkmcnt(1)
	v_mfma_f32_32x32x16_bf16 v[66:81], v[134:137], v[238:241], v[66:81]
	v_mfma_f32_32x32x16_bf16 v[82:97], v[134:137], v[246:249], v[82:97]
	s_waitcnt lgkmcnt(0)
	v_mfma_f32_32x32x16_bf16 v[98:113], v[138:141], v[238:241], v[98:113]
	v_mfma_f32_32x32x16_bf16 v[214:229], v[138:141], v[246:249], v[214:229]
	s_waitcnt vmcnt(6)
	s_barrier
	ds_read_b128 v[114:117], v142 offset:16384
	ds_read_b128 v[230:233], v144 offset:8192
	ds_read_b128 v[234:237], v144 offset:10240
	ds_read_b128 v[118:121], v142 offset:18432
	ds_read_b128 v[134:137], v142 offset:24576
	ds_read_b128 v[138:141], v142 offset:26624
	ds_read_b128 v[238:241], v145 offset:8192
	ds_read_b128 v[246:249], v145 offset:10240
	s_add_u32 m0, s68, 0
	s_nop 0
	global_load_lds_dwordx4 v126, s[64:65]
	s_add_u32 m0, s68, 4096
	s_nop 0
	global_load_lds_dwordx4 v127, s[64:65]
	s_add_u32 m0, s68, 8192
	s_nop 0
	global_load_lds_dwordx4 v128, s[64:65]
	s_add_u32 m0, s68, 12288
	s_nop 0
	global_load_lds_dwordx4 v129, s[64:65]
	s_add_u32 m0, s68, 49152
	s_nop 0
	global_load_lds_dwordx4 v126, s[66:67]
	s_add_u32 m0, s68, 53248
	s_nop 0
	global_load_lds_dwordx4 v127, s[66:67]
	s_add_u32 s64, s64, 64
	s_addc_u32 s65, s65, 0
	s_add_u32 s66, s66, 64
	s_addc_u32 s67, s67, 0
	s_waitcnt lgkmcnt(6)
	v_mfma_f32_32x32x16_bf16 v[2:17], v[114:117], v[230:233], v[2:17]
	s_waitcnt lgkmcnt(5)
	v_mfma_f32_32x32x16_bf16 v[18:33], v[114:117], v[234:237], v[18:33]
	ds_read_b128 v[114:117], v143 offset:16384
	s_waitcnt lgkmcnt(5)
	v_mfma_f32_32x32x16_bf16 v[34:49], v[118:121], v[230:233], v[34:49]
	v_mfma_f32_32x32x16_bf16 v[50:65], v[118:121], v[234:237], v[50:65]
	ds_read_b128 v[118:121], v143 offset:18432
	s_waitcnt lgkmcnt(5)
	v_mfma_f32_32x32x16_bf16 v[66:81], v[134:137], v[230:233], v[66:81]
	v_mfma_f32_32x32x16_bf16 v[82:97], v[134:137], v[234:237], v[82:97]
	ds_read_b128 v[134:137], v143 offset:24576
	s_waitcnt lgkmcnt(5)
	v_mfma_f32_32x32x16_bf16 v[98:113], v[138:141], v[230:233], v[98:113]
	v_mfma_f32_32x32x16_bf16 v[214:229], v[138:141], v[234:237], v[214:229]
	ds_read_b128 v[138:141], v143 offset:26624
	s_waitcnt lgkmcnt(3)
	v_mfma_f32_32x32x16_bf16 v[2:17], v[114:117], v[238:241], v[2:17]
	v_mfma_f32_32x32x16_bf16 v[18:33], v[114:117], v[246:249], v[18:33]
	s_waitcnt lgkmcnt(2)
	v_mfma_f32_32x32x16_bf16 v[34:49], v[118:121], v[238:241], v[34:49]
	v_mfma_f32_32x32x16_bf16 v[50:65], v[118:121], v[246:249], v[50:65]
	s_waitcnt lgkmcnt(1)
	v_mfma_f32_32x32x16_bf16 v[66:81], v[134:137], v[238:241], v[66:81]
	v_mfma_f32_32x32x16_bf16 v[82:97], v[134:137], v[246:249], v[82:97]
	s_waitcnt lgkmcnt(0)
	v_mfma_f32_32x32x16_bf16 v[98:113], v[138:141], v[238:241], v[98:113]
	v_mfma_f32_32x32x16_bf16 v[214:229], v[138:141], v[246:249], v[214:229]
	s_waitcnt vmcnt(6)
	s_barrier
; #define MFMA(a, b, c) __builtin_amdgcn_mfma_f32_32x32x16_bf16((a), (b), (c), 0, 0, 0)
; template <int AI, int BI>
; DI void gemm_tile(const u16* __restrict__ A, int lda, const u16* __restrict__ B, int ldb, int nk, bool swap,
;                   f32x16 (&acc)[AI][BI], char* lds) {
;     ...
;   for (int kt = 0; kt < nk; ++kt) {
;     const char* cur = lds + (kt & 1) * 32768;
;     if (kt + 1 < nk) gemm_stage<AI, BI>(A + (kt + 1) * 64, lda, B + (kt + 1) * 64, ldb, lds + ((kt + 1) & 1) * 32768, tid);
; #pragma unroll
;     for (int ks = 0; ks < 4; ++ks) {
;       const int co = ((ks * 2 + h) ^ sw) << 4;
;       s16x8 fa[AI], fb[BI];
; #pragma unroll
;       for (int i = 0; i < AI; ++i) fa[i] = *(const s16x8*)(cur + offA + i * 4096 + co);
; #pragma unroll
;       for (int i = 0; i < BI; ++i) fb[i] = *(const s16x8*)(cur + offB + i * 4096 + co);
; #pragma unroll
;       for (int i = 0; i < AI; ++i)
; #pragma unroll
;         for (int j = 0; j < BI; ++j) acc[i][j] = MFMA(fa[i], fb[j], acc[i][j]);
;     }
;     asm volatile("s_waitcnt vmcnt(0)" ::: "memory");
;     __syncthreads();
;   }
	ds_read_b128 v[114:117], v142 offset:32768
	ds_read_b128 v[230:233], v144 offset:16512
	ds_read_b128 v[234:237], v144 offset:18560
	ds_read_b128 v[118:121], v142 offset:34816
	ds_read_b128 v[134:137], v142 offset:40960
	ds_read_b128 v[138:141], v142 offset:43008
	ds_read_b128 v[238:241], v145 offset:16512
	ds_read_b128 v[246:249], v145 offset:18560
	s_add_u32 m0, s68, 16384
	s_nop 0
	global_load_lds_dwordx4 v126, s[64:65]
	s_add_u32 m0, s68, 20480
	s_nop 0
	global_load_lds_dwordx4 v127, s[64:65]
	s_add_u32 m0, s68, 24576
	s_nop 0
	global_load_lds_dwordx4 v128, s[64:65]
	s_add_u32 m0, s68, 28672
	s_nop 0
	global_load_lds_dwordx4 v129, s[64:65]
	s_add_u32 m0, s68, 57344
	s_nop 0
	global_load_lds_dwordx4 v126, s[66:67]
	s_add_u32 m0, s68, 61440
	s_nop 0
	global_load_lds_dwordx4 v127, s[66:67]
	s_add_u32 s64, s64, 64
	s_addc_u32 s65, s65, 0
	s_add_u32 s66, s66, 64
	s_addc_u32 s67, s67, 0
	s_waitcnt lgkmcnt(6)
	v_mfma_f32_32x32x16_bf16 v[2:17], v[114:117], v[230:233], v[2:17]
	s_waitcnt lgkmcnt(5)
	v_mfma_f32_32x32x16_bf16 v[18:33], v[114:117], v[234:237], v[18:33]
	ds_read_b128 v[114:117], v143 offset:32768
	s_waitcnt lgkmcnt(5)
	v_mfma_f32_32x32x16_bf16 v[34:49], v[118:121], v[230:233], v[34:49]
	v_mfma_f32_32x32x16_bf16 v[50:65], v[118:121], v[234:237], v[50:65]
	ds_read_b128 v[118:121], v143 offset:34816
	s_waitcnt lgkmcnt(5)
	v_mfma_f32_32x32x16_bf16 v[66:81], v[134:137], v[230:233], v[66:81]
	v_mfma_f32_32x32x16_bf16 v[82:97], v[134:137], v[234:237], v[82:97]
	ds_read_b128 v[134:137], v143 offset:40960
	s_waitcnt lgkmcnt(5)
	v_mfma_f32_32x32x16_bf16 v[98:113], v[138:141], v[230:233], v[98:113]
	v_mfma_f32_32x32x16_bf16 v[214:229], v[138:141], v[234:237], v[214:229]
	ds_read_b128 v[138:141], v143 offset:43008
	s_waitcnt lgkmcnt(3)
	v_mfma_f32_32x32x16_bf16 v[2:17], v[114:117], v[238:241], v[2:17]
	v_mfma_f32_32x32x16_bf16 v[18:33], v[114:117], v[246:249], v[18:33]
	s_waitcnt lgkmcnt(2)
	v_mfma_f32_32x32x16_bf16 v[34:49], v[118:121], v[238:241], v[34:49]
	v_mfma_f32_32x32x16_bf16 v[50:65], v[118:121], v[246:249], v[50:65]
	s_waitcnt lgkmcnt(1)
	v_mfma_f32_32x32x16_bf16 v[66:81], v[134:137], v[238:241], v[66:81]
	v_mfma_f32_32x32x16_bf16 v[82:97], v[134:137], v[246:249], v[82:97]
	s_waitcnt lgkmcnt(0)
	v_mfma_f32_32x32x16_bf16 v[98:113], v[138:141], v[238:241], v[98:113]
	v_mfma_f32_32x32x16_bf16 v[214:229], v[138:141], v[246:249], v[214:229]
	s_sub_u32 s69, s69, 1
	s_cmp_lg_u32 s69, 0
	s_cbranch_scc1 .Ldn2_kloop
	s_waitcnt vmcnt(6)
	s_barrier
	ds_read_b128 v[114:117], v142 offset:0
	ds_read_b128 v[230:233], v144 offset:0
	ds_read_b128 v[234:237], v144 offset:2048
	ds_read_b128 v[118:121], v142 offset:2048
	ds_read_b128 v[134:137], v142 offset:8192
	ds_read_b128 v[138:141], v142 offset:10240
	ds_read_b128 v[238:241], v145 offset:0
	ds_read_b128 v[246:249], v145 offset:2048
	s_add_u32 m0, s68, 32768
	s_nop 0
	global_load_lds_dwordx4 v126, s[64:65]
	s_add_u32 m0, s68, 36864
	s_nop 0
	global_load_lds_dwordx4 v127, s[64:65]
	s_add_u32 m0, s68, 40960
	s_nop 0
	global_load_lds_dwordx4 v128, s[64:65]
	s_add_u32 m0, s68, 45056
	s_nop 0
	global_load_lds_dwordx4 v129, s[64:65]
	s_add_u32 m0, s68, 65664
	s_nop 0
	global_load_lds_dwordx4 v126, s[66:67]
	s_add_u32 m0, s68, 69760
	s_nop 0
	global_load_lds_dwordx4 v127, s[66:67]
	s_add_u32 s64, s64, 64
	s_addc_u32 s65, s65, 0
	s_add_u32 s66, s66, 64
	s_addc_u32 s67, s67, 0
	s_waitcnt lgkmcnt(6)
	v_mfma_f32_32x32x16_bf16 v[2:17], v[114:117], v[230:233], v[2:17]
	s_waitcnt lgkmcnt(5)
	v_mfma_f32_32x32x16_bf16 v[18:33], v[114:117], v[234:237], v[18:33]
	ds_read_b128 v[114:117], v143 offset:0
	s_waitcnt lgkmcnt(5)
	v_mfma_f32_32x32x16_bf16 v[34:49], v[118:121], v[230:233], v[34:49]
	v_mfma_f32_32x32x16_bf16 v[50:65], v[118:121], v[234:237], v[50:65]
	ds_read_b128 v[118:121], v143 offset:2048
	s_waitcnt lgkmcnt(5)
	v_mfma_f32_32x32x16_bf16 v[66:81], v[134:137], v[230:233], v[66:81]
	v_mfma_f32_32x32x16_bf16 v[82:97], v[134:137], v[234:237], v[82:97]
	ds_read_b128 v[134:137], v143 offset:8192
	s_waitcnt lgkmcnt(5)
	v_mfma_f32_32x32x16_bf16 v[98:113], v[138:141], v[230:233], v[98:113]
	v_mfma_f32_32x32x16_bf16 v[214:229], v[138:141], v[234:237], v[214:229]
	ds_read_b128 v[138:141], v143 offset:10240
	s_waitcnt lgkmcnt(3)
	v_mfma_f32_32x32x16_bf16 v[2:17], v[114:117], v[238:241], v[2:17]
	v_mfma_f32_32x32x16_bf16 v[18:33], v[114:117], v[246:249], v[18:33]
	s_waitcnt lgkmcnt(2)
	v_mfma_f32_32x32x16_bf16 v[34:49], v[118:121], v[238:241], v[34:49]
	v_mfma_f32_32x32x16_bf16 v[50:65], v[118:121], v[246:249], v[50:65]
	s_waitcnt lgkmcnt(1)
	v_mfma_f32_32x32x16_bf16 v[66:81], v[134:137], v[238:241], v[66:81]
	v_mfma_f32_32x32x16_bf16 v[82:97], v[134:137], v[246:249], v[82:97]
	s_waitcnt lgkmcnt(0)
	v_mfma_f32_32x32x16_bf16 v[98:113], v[138:141], v[238:241], v[98:113]
	v_mfma_f32_32x32x16_bf16 v[214:229], v[138:141], v[246:249], v[214:229]
	s_waitcnt vmcnt(6)
	s_barrier
; #define MFMA(a, b, c) __builtin_amdgcn_mfma_f32_32x32x16_bf16((a), (b), (c), 0, 0, 0)
; template <int AI, int BI>
; DI void gemm_tile(const u16* __restrict__ A, int lda, const u16* __restrict__ B, int ldb, int nk, bool swap,
;                   f32x16 (&acc)[AI][BI], char* lds) {
;     ...
;   for (int kt = 0; kt < nk; ++kt) {
;     const char* cur = lds + (kt & 1) * 32768;
;     if (kt + 1 < nk) gemm_stage<AI, BI>(A + (kt + 1) * 64, lda, B + (kt + 1) * 64, ldb, lds + ((kt + 1) & 1) * 32768, tid);
; #pragma unroll
;     for (int ks = 0; ks < 4; ++ks) {
;       const int co = ((ks * 2 + h) ^ sw) << 4;
;       s16x8 fa[AI], fb[BI];
; #pragma unroll
;       for (int i = 0; i < AI; ++i) fa[i] = *(const s16x8*)(cur + offA + i * 4096 + co);
; #pragma unroll
;       for (int i = 0; i < BI; ++i) fb[i] = *(const s16x8*)(cur + offB + i * 4096 + co);
; #pragma unroll
;       for (int i = 0; i < AI; ++i)
; #pragma unroll
;         for (int j = 0; j < BI; ++j) acc[i][j] = MFMA(fa[i], fb[j], acc[i][j]);
;     }
;     asm volatile("s_waitcnt vmcnt(0)" ::: "memory");
;     __syncthreads();
;   }
	ds_read_b128 v[114:117], v142 offset:16384
	ds_read_b128 v[230:233], v144 offset:8192
	ds_read_b128 v[234:237], v144 offset:10240
	ds_read_b128 v[118:121], v142 offset:18432
	ds_read_b128 v[134:137], v142 offset:24576
	ds_read_b128 v[138:141], v142 offset:26624
	ds_read_b128 v[238:241], v145 offset:8192
	ds_read_b128 v[246:249], v145 offset:10240
	s_add_u32 m0, s68, 0
	s_nop 0
	global_load_lds_dwordx4 v126, s[64:65]
	s_add_u32 m0, s68, 4096
	s_nop 0
	global_load_lds_dwordx4 v127, s[64:65]
	s_add_u32 m0, s68, 8192
	s_nop 0
	global_load_lds_dwordx4 v128, s[64:65]
	s_add_u32 m0, s68, 12288
	s_nop 0
	global_load_lds_dwordx4 v129, s[64:65]
	s_add_u32 m0, s68, 49152
	s_nop 0
	global_load_lds_dwordx4 v126, s[66:67]
	s_add_u32 m0, s68, 53248
	s_nop 0
	global_load_lds_dwordx4 v127, s[66:67]
	s_add_u32 s64, s64, 64
	s_addc_u32 s65, s65, 0
	s_add_u32 s66, s66, 64
	s_addc_u32 s67, s67, 0
	s_waitcnt lgkmcnt(6)
	v_mfma_f32_32x32x16_bf16 v[2:17], v[114:117], v[230:233], v[2:17]
	s_waitcnt lgkmcnt(5)
	v_mfma_f32_32x32x16_bf16 v[18:33], v[114:117], v[234:237], v[18:33]
	ds_read_b128 v[114:117], v143 offset:16384
	s_waitcnt lgkmcnt(5)
	v_mfma_f32_32x32x16_bf16 v[34:49], v[118:121], v[230:233], v[34:49]
	v_mfma_f32_32x32x16_bf16 v[50:65], v[118:121], v[234:237], v[50:65]
	ds_read_b128 v[118:121], v143 offset:18432
	s_waitcnt lgkmcnt(5)
	v_mfma_f32_32x32x16_bf16 v[66:81], v[134:137], v[230:233], v[66:81]
	v_mfma_f32_32x32x16_bf16 v[82:97], v[134:137], v[234:237], v[82:97]
	ds_read_b128 v[134:137], v143 offset:24576
	s_waitcnt lgkmcnt(5)
	v_mfma_f32_32x32x16_bf16 v[98:113], v[138:141], v[230:233], v[98:113]
	v_mfma_f32_32x32x16_bf16 v[214:229], v[138:141], v[234:237], v[214:229]
	ds_read_b128 v[138:141], v143 offset:26624
	s_waitcnt lgkmcnt(3)
	v_mfma_f32_32x32x16_bf16 v[2:17], v[114:117], v[238:241], v[2:17]
	v_mfma_f32_32x32x16_bf16 v[18:33], v[114:117], v[246:249], v[18:33]
	s_waitcnt lgkmcnt(2)
	v_mfma_f32_32x32x16_bf16 v[34:49], v[118:121], v[238:241], v[34:49]
	v_mfma_f32_32x32x16_bf16 v[50:65], v[118:121], v[246:249], v[50:65]
	s_waitcnt lgkmcnt(1)
	v_mfma_f32_32x32x16_bf16 v[66:81], v[134:137], v[238:241], v[66:81]
	v_mfma_f32_32x32x16_bf16 v[82:97], v[134:137], v[246:249], v[82:97]
	s_waitcnt lgkmcnt(0)
	v_mfma_f32_32x32x16_bf16 v[98:113], v[138:141], v[238:241], v[98:113]
	v_mfma_f32_32x32x16_bf16 v[214:229], v[138:141], v[246:249], v[214:229]
	s_waitcnt vmcnt(6)
	s_barrier
	ds_read_b128 v[114:117], v142 offset:32768
	ds_read_b128 v[230:233], v144 offset:16512
	ds_read_b128 v[234:237], v144 offset:18560
	ds_read_b128 v[118:121], v142 offset:34816
	ds_read_b128 v[134:137], v142 offset:40960
	ds_read_b128 v[138:141], v142 offset:43008
	ds_read_b128 v[238:241], v145 offset:16512
	ds_read_b128 v[246:249], v145 offset:18560
	s_waitcnt lgkmcnt(6)
	v_mfma_f32_32x32x16_bf16 v[2:17], v[114:117], v[230:233], v[2:17]
	s_waitcnt lgkmcnt(5)
	v_mfma_f32_32x32x16_bf16 v[18:33], v[114:117], v[234:237], v[18:33]
	ds_read_b128 v[114:117], v143 offset:32768
	s_waitcnt lgkmcnt(5)
	v_mfma_f32_32x32x16_bf16 v[34:49], v[118:121], v[230:233], v[34:49]
	v_mfma_f32_32x32x16_bf16 v[50:65], v[118:121], v[234:237], v[50:65]
	ds_read_b128 v[118:121], v143 offset:34816
	s_waitcnt lgkmcnt(5)
	v_mfma_f32_32x32x16_bf16 v[66:81], v[134:137], v[230:233], v[66:81]
	v_mfma_f32_32x32x16_bf16 v[82:97], v[134:137], v[234:237], v[82:97]
	ds_read_b128 v[134:137], v143 offset:40960
	s_waitcnt lgkmcnt(5)
	v_mfma_f32_32x32x16_bf16 v[98:113], v[138:141], v[230:233], v[98:113]
	v_mfma_f32_32x32x16_bf16 v[214:229], v[138:141], v[234:237], v[214:229]
	ds_read_b128 v[138:141], v143 offset:43008
	s_waitcnt lgkmcnt(3)
	v_mfma_f32_32x32x16_bf16 v[2:17], v[114:117], v[238:241], v[2:17]
	v_mfma_f32_32x32x16_bf16 v[18:33], v[114:117], v[246:249], v[18:33]
	s_waitcnt lgkmcnt(2)
	v_mfma_f32_32x32x16_bf16 v[34:49], v[118:121], v[238:241], v[34:49]
	v_mfma_f32_32x32x16_bf16 v[50:65], v[118:121], v[246:249], v[50:65]
	s_waitcnt lgkmcnt(1)
	v_mfma_f32_32x32x16_bf16 v[66:81], v[134:137], v[238:241], v[66:81]
	v_mfma_f32_32x32x16_bf16 v[82:97], v[134:137], v[246:249], v[82:97]
	s_waitcnt lgkmcnt(0)
	v_mfma_f32_32x32x16_bf16 v[98:113], v[138:141], v[238:241], v[98:113]
	v_mfma_f32_32x32x16_bf16 v[214:229], v[138:141], v[246:249], v[214:229]
	s_waitcnt vmcnt(0)
	s_barrier
	ds_read_b128 v[114:117], v142 offset:0
	ds_read_b128 v[230:233], v144 offset:0
	ds_read_b128 v[234:237], v144 offset:2048
	ds_read_b128 v[118:121], v142 offset:2048
	ds_read_b128 v[134:137], v142 offset:8192
	ds_read_b128 v[138:141], v142 offset:10240
	ds_read_b128 v[238:241], v145 offset:0
	ds_read_b128 v[246:249], v145 offset:2048
	s_waitcnt lgkmcnt(6)
	v_mfma_f32_32x32x16_bf16 v[2:17], v[114:117], v[230:233], v[2:17]
	s_waitcnt lgkmcnt(5)
	v_mfma_f32_32x32x16_bf16 v[18:33], v[114:117], v[234:237], v[18:33]
	ds_read_b128 v[114:117], v143 offset:0
	s_waitcnt lgkmcnt(5)
	v_mfma_f32_32x32x16_bf16 v[34:49], v[118:121], v[230:233], v[34:49]
	v_mfma_f32_32x32x16_bf16 v[50:65], v[118:121], v[234:237], v[50:65]
	ds_read_b128 v[118:121], v143 offset:2048
	s_waitcnt lgkmcnt(5)
	v_mfma_f32_32x32x16_bf16 v[66:81], v[134:137], v[230:233], v[66:81]
	v_mfma_f32_32x32x16_bf16 v[82:97], v[134:137], v[234:237], v[82:97]
	ds_read_b128 v[134:137], v143 offset:8192
	s_waitcnt lgkmcnt(5)
	v_mfma_f32_32x32x16_bf16 v[98:113], v[138:141], v[230:233], v[98:113]
	v_mfma_f32_32x32x16_bf16 v[214:229], v[138:141], v[234:237], v[214:229]
	ds_read_b128 v[138:141], v143 offset:10240
	s_waitcnt lgkmcnt(3)
	v_mfma_f32_32x32x16_bf16 v[2:17], v[114:117], v[238:241], v[2:17]
	v_mfma_f32_32x32x16_bf16 v[18:33], v[114:117], v[246:249], v[18:33]
	s_waitcnt lgkmcnt(2)
	v_mfma_f32_32x32x16_bf16 v[34:49], v[118:121], v[238:241], v[34:49]
	v_mfma_f32_32x32x16_bf16 v[50:65], v[118:121], v[246:249], v[50:65]
	s_waitcnt lgkmcnt(1)
	v_mfma_f32_32x32x16_bf16 v[66:81], v[134:137], v[238:241], v[66:81]
	v_mfma_f32_32x32x16_bf16 v[82:97], v[134:137], v[246:249], v[82:97]
	s_waitcnt lgkmcnt(0)
	v_mfma_f32_32x32x16_bf16 v[98:113], v[138:141], v[238:241], v[98:113]
	v_mfma_f32_32x32x16_bf16 v[214:229], v[138:141], v[246:249], v[214:229]
	s_nop 7
	s_nop 7
	s_barrier
; #define GAS __attribute__((address_space(1)))
; DI int opaque0() { int z = 0; asm volatile("" : "+v"(z)); return z; }
; template <int AI, int BI>
; DI void dn_tile(const Params& p, char* wsb, int layer, int sub, bool final_out, int m0, int n0, char* lds) {
;     ...
;   const int m0e = m0 + opaque0();
;   const int mr = m0 < TL ? (m0 >> 11) : 8;
;   const float* gate = mods + (size_t)mr * 9216 + (2 + 6 * sub) * 1024;
;   GAS float* xsu = uptr(xs);
;   GAS float* outu = uptr(p.out);
; #pragma unroll
;   for (int bi = 0; bi < BI; ++bi) {
;     const int n = n0 + wb * 32 * BI + bi * 32 + r;
;     const float gv = 0.5f * gate[n];
;     const unsigned ib = (unsigned)((m0e + wa * 32 * AI + 4 * h) * 1024 + n);
; #pragma unroll
;     for (int ai = 0; ai < AI; ++ai)
; #pragma unroll
;       for (int reg = 0; reg < 16; ++reg) {
;         const unsigned idx = ib + (unsigned)((ai * 32 + (reg & 3) + 8 * (reg >> 2)) * 1024);
;         float v = xsu[idx] + gv * acc[ai][bi][reg];
;         if (final_out) outu[idx] = v; else xsu[idx] = v;
;         if ((reg & 7) == 7) __builtin_amdgcn_sched_barrier(0);
;       }
;   }
	v_and_b32_e32 v0, 31, v178
	v_and_b32_e32 v123, 64, v178
	v_or_b32_e32 v123, v123, v0
	v_bfe_u32 v0, v178, 5, 1
	v_bfe_u32 v122, v178, 7, 1
	v_lshlrev_b32_e32 v122, 6, v122
	v_lshl_add_u32 v122, v0, 2, v122
	v_lshl_add_u32 v122, v122, 10, v123
	v_lshlrev_b32_e32 v122, 2, v122
	s_lshl_b32 s74, s73, 7
	v_add_u32_e32 v123, s74, v123
	v_lshlrev_b32_e32 v123, 2, v123
	s_lshr_b32 s75, s72, 3
	s_mul_i32 s75, s75, 0x9000
	s_add_u32 s76, s34, s75
	s_addc_u32 s77, s35, 0
	s_add_u32 s76, s76, 0xc000
	s_addc_u32 s77, s77, 0
	global_load_dword v124, v123, s[76:77]
	global_load_dword v142, v123, s[76:77] offset:128
	s_lshl_b32 s75, s72, 20
	s_lshl_b32 s74, s73, 9
	s_add_u32 s75, s75, s74
	s_add_u32 s80, s8, s75
	s_addc_u32 s81, s9, 0
	s_and_b64 s[84:85], s[48:49], exec
	s_cselect_b32 s84, s8, s24
	s_cselect_b32 s85, s9, s25
	s_add_u32 s82, s84, s75
	s_addc_u32 s83, s85, 0
	s_waitcnt vmcnt(0)
	v_mul_f32_e32 v124, 0.5, v124
	v_mul_f32_e32 v142, 0.5, v142
	s_add_u32 s52, s80, 0
	s_addc_u32 s53, s81, 0
	global_load_dword v114, v122, s[52:53]
	global_load_dword v115, v122, s[52:53] offset:128
	s_add_u32 s52, s52, 4096
	s_addc_u32 s53, s53, 0
	global_load_dword v116, v122, s[52:53]
	global_load_dword v117, v122, s[52:53] offset:128
	s_add_u32 s52, s52, 4096
	s_addc_u32 s53, s53, 0
	global_load_dword v118, v122, s[52:53]
	global_load_dword v119, v122, s[52:53] offset:128
	s_add_u32 s52, s52, 4096
	s_addc_u32 s53, s53, 0
	global_load_dword v120, v122, s[52:53]
	global_load_dword v121, v122, s[52:53] offset:128
	s_add_u32 s52, s52, 20480
	s_addc_u32 s53, s53, 0
	global_load_dword v134, v122, s[52:53]
	global_load_dword v135, v122, s[52:53] offset:128
	s_add_u32 s52, s52, 4096
	s_addc_u32 s53, s53, 0
	global_load_dword v136, v122, s[52:53]
	global_load_dword v137, v122, s[52:53] offset:128
	s_add_u32 s52, s52, 4096
	s_addc_u32 s53, s53, 0
	global_load_dword v138, v122, s[52:53]
	global_load_dword v139, v122, s[52:53] offset:128
	s_add_u32 s52, s52, 4096
	s_addc_u32 s53, s53, 0
	global_load_dword v140, v122, s[52:53]
	global_load_dword v141, v122, s[52:53] offset:128
	s_waitcnt vmcnt(0)
	v_fmac_f32_e32 v114, v2, v124
	v_fmac_f32_e32 v115, v18, v142
	v_fmac_f32_e32 v116, v3, v124
	v_fmac_f32_e32 v117, v19, v142
	v_fmac_f32_e32 v118, v4, v124
	v_fmac_f32_e32 v119, v20, v142
	v_fmac_f32_e32 v120, v5, v124
	v_fmac_f32_e32 v121, v21, v142
	v_fmac_f32_e32 v134, v6, v124
	v_fmac_f32_e32 v135, v22, v142
	v_fmac_f32_e32 v136, v7, v124
	v_fmac_f32_e32 v137, v23, v142
	v_fmac_f32_e32 v138, v8, v124
	v_fmac_f32_e32 v139, v24, v142
	v_fmac_f32_e32 v140, v9, v124
	v_fmac_f32_e32 v141, v25, v142
	s_add_u32 s52, s82, 0
	s_addc_u32 s53, s83, 0
	global_store_dword v122, v114, s[52:53]
	global_store_dword v122, v115, s[52:53] offset:128
	s_add_u32 s52, s52, 4096
	s_addc_u32 s53, s53, 0
	global_store_dword v122, v116, s[52:53]
	global_store_dword v122, v117, s[52:53] offset:128
	s_add_u32 s52, s52, 4096
	s_addc_u32 s53, s53, 0
	global_store_dword v122, v118, s[52:53]
	global_store_dword v122, v119, s[52:53] offset:128
	s_add_u32 s52, s52, 4096
	s_addc_u32 s53, s53, 0
	global_store_dword v122, v120, s[52:53]
	global_store_dword v122, v121, s[52:53] offset:128
	s_add_u32 s52, s52, 20480
	s_addc_u32 s53, s53, 0
	global_store_dword v122, v134, s[52:53]
	global_store_dword v122, v135, s[52:53] offset:128
	s_add_u32 s52, s52, 4096
	s_addc_u32 s53, s53, 0
	global_store_dword v122, v136, s[52:53]
	global_store_dword v122, v137, s[52:53] offset:128
	s_add_u32 s52, s52, 4096
	s_addc_u32 s53, s53, 0
	global_store_dword v122, v138, s[52:53]
	global_store_dword v122, v139, s[52:53] offset:128
	s_add_u32 s52, s52, 4096
	s_addc_u32 s53, s53, 0
	global_store_dword v122, v140, s[52:53]
	global_store_dword v122, v141, s[52:53] offset:128
	s_add_u32 s52, s80, 65536
	s_addc_u32 s53, s81, 0
	global_load_dword v114, v122, s[52:53]
	global_load_dword v115, v122, s[52:53] offset:128
	s_add_u32 s52, s52, 4096
	s_addc_u32 s53, s53, 0
	global_load_dword v116, v122, s[52:53]
	global_load_dword v117, v122, s[52:53] offset:128
	s_add_u32 s52, s52, 4096
	s_addc_u32 s53, s53, 0
	global_load_dword v118, v122, s[52:53]
	global_load_dword v119, v122, s[52:53] offset:128
	s_add_u32 s52, s52, 4096
	s_addc_u32 s53, s53, 0
	global_load_dword v120, v122, s[52:53]
	global_load_dword v121, v122, s[52:53] offset:128
	s_add_u32 s52, s52, 20480
	s_addc_u32 s53, s53, 0
	global_load_dword v134, v122, s[52:53]
	global_load_dword v135, v122, s[52:53] offset:128
	s_add_u32 s52, s52, 4096
	s_addc_u32 s53, s53, 0
	global_load_dword v136, v122, s[52:53]
	global_load_dword v137, v122, s[52:53] offset:128
	s_add_u32 s52, s52, 4096
	s_addc_u32 s53, s53, 0
	global_load_dword v138, v122, s[52:53]
	global_load_dword v139, v122, s[52:53] offset:128
	s_add_u32 s52, s52, 4096
	s_addc_u32 s53, s53, 0
	global_load_dword v140, v122, s[52:53]
	global_load_dword v141, v122, s[52:53] offset:128
	s_waitcnt vmcnt(0)
; template <int AI, int BI>
; DI void dn_tile(const Params& p, char* wsb, int layer, int sub, bool final_out, int m0, int n0, char* lds) {
;     ...
; #pragma unroll
;   for (int bi = 0; bi < BI; ++bi) {
;     const int n = n0 + wb * 32 * BI + bi * 32 + r;
;     const float gv = 0.5f * gate[n];
;     const unsigned ib = (unsigned)((m0e + wa * 32 * AI + 4 * h) * 1024 + n);
; #pragma unroll
;     for (int ai = 0; ai < AI; ++ai)
; #pragma unroll
;       for (int reg = 0; reg < 16; ++reg) {
;         const unsigned idx = ib + (unsigned)((ai * 32 + (reg & 3) + 8 * (reg >> 2)) * 1024);
;         float v = xsu[idx] + gv * acc[ai][bi][reg];
;         if (final_out) outu[idx] = v; else xsu[idx] = v;
;         if ((reg & 7) == 7) __builtin_amdgcn_sched_barrier(0);
;       }
;   }
	v_fmac_f32_e32 v114, v10, v124
	v_fmac_f32_e32 v115, v26, v142
	v_fmac_f32_e32 v116, v11, v124
	v_fmac_f32_e32 v117, v27, v142
	v_fmac_f32_e32 v118, v12, v124
	v_fmac_f32_e32 v119, v28, v142
	v_fmac_f32_e32 v120, v13, v124
	v_fmac_f32_e32 v121, v29, v142
	v_fmac_f32_e32 v134, v14, v124
	v_fmac_f32_e32 v135, v30, v142
	v_fmac_f32_e32 v136, v15, v124
	v_fmac_f32_e32 v137, v31, v142
	v_fmac_f32_e32 v138, v16, v124
	v_fmac_f32_e32 v139, v32, v142
	v_fmac_f32_e32 v140, v17, v124
	v_fmac_f32_e32 v141, v33, v142
	s_add_u32 s52, s82, 65536
	s_addc_u32 s53, s83, 0
	global_store_dword v122, v114, s[52:53]
	global_store_dword v122, v115, s[52:53] offset:128
	s_add_u32 s52, s52, 4096
	s_addc_u32 s53, s53, 0
	global_store_dword v122, v116, s[52:53]
	global_store_dword v122, v117, s[52:53] offset:128
	s_add_u32 s52, s52, 4096
	s_addc_u32 s53, s53, 0
	global_store_dword v122, v118, s[52:53]
	global_store_dword v122, v119, s[52:53] offset:128
	s_add_u32 s52, s52, 4096
	s_addc_u32 s53, s53, 0
	global_store_dword v122, v120, s[52:53]
	global_store_dword v122, v121, s[52:53] offset:128
	s_add_u32 s52, s52, 20480
	s_addc_u32 s53, s53, 0
	global_store_dword v122, v134, s[52:53]
	global_store_dword v122, v135, s[52:53] offset:128
	s_add_u32 s52, s52, 4096
	s_addc_u32 s53, s53, 0
	global_store_dword v122, v136, s[52:53]
	global_store_dword v122, v137, s[52:53] offset:128
	s_add_u32 s52, s52, 4096
	s_addc_u32 s53, s53, 0
	global_store_dword v122, v138, s[52:53]
	global_store_dword v122, v139, s[52:53] offset:128
	s_add_u32 s52, s52, 4096
	s_addc_u32 s53, s53, 0
	global_store_dword v122, v140, s[52:53]
	global_store_dword v122, v141, s[52:53] offset:128
	s_add_u32 s52, s80, 131072
	s_addc_u32 s53, s81, 0
	global_load_dword v114, v122, s[52:53]
	global_load_dword v115, v122, s[52:53] offset:128
	s_add_u32 s52, s52, 4096
	s_addc_u32 s53, s53, 0
	global_load_dword v116, v122, s[52:53]
	global_load_dword v117, v122, s[52:53] offset:128
	s_add_u32 s52, s52, 4096
	s_addc_u32 s53, s53, 0
	global_load_dword v118, v122, s[52:53]
	global_load_dword v119, v122, s[52:53] offset:128
	s_add_u32 s52, s52, 4096
	s_addc_u32 s53, s53, 0
	global_load_dword v120, v122, s[52:53]
	global_load_dword v121, v122, s[52:53] offset:128
	s_add_u32 s52, s52, 20480
	s_addc_u32 s53, s53, 0
	global_load_dword v134, v122, s[52:53]
	global_load_dword v135, v122, s[52:53] offset:128
	s_add_u32 s52, s52, 4096
	s_addc_u32 s53, s53, 0
	global_load_dword v136, v122, s[52:53]
	global_load_dword v137, v122, s[52:53] offset:128
	s_add_u32 s52, s52, 4096
	s_addc_u32 s53, s53, 0
	global_load_dword v138, v122, s[52:53]
	global_load_dword v139, v122, s[52:53] offset:128
	s_add_u32 s52, s52, 4096
	s_addc_u32 s53, s53, 0
	global_load_dword v140, v122, s[52:53]
	global_load_dword v141, v122, s[52:53] offset:128
	s_waitcnt vmcnt(0)
	v_fmac_f32_e32 v114, v34, v124
	v_fmac_f32_e32 v115, v50, v142
	v_fmac_f32_e32 v116, v35, v124
	v_fmac_f32_e32 v117, v51, v142
	v_fmac_f32_e32 v118, v36, v124
	v_fmac_f32_e32 v119, v52, v142
	v_fmac_f32_e32 v120, v37, v124
	v_fmac_f32_e32 v121, v53, v142
	v_fmac_f32_e32 v134, v38, v124
	v_fmac_f32_e32 v135, v54, v142
	v_fmac_f32_e32 v136, v39, v124
	v_fmac_f32_e32 v137, v55, v142
	v_fmac_f32_e32 v138, v40, v124
	v_fmac_f32_e32 v139, v56, v142
	v_fmac_f32_e32 v140, v41, v124
	v_fmac_f32_e32 v141, v57, v142
	s_add_u32 s52, s82, 131072
	s_addc_u32 s53, s83, 0
	global_store_dword v122, v114, s[52:53]
	global_store_dword v122, v115, s[52:53] offset:128
	s_add_u32 s52, s52, 4096
	s_addc_u32 s53, s53, 0
	global_store_dword v122, v116, s[52:53]
	global_store_dword v122, v117, s[52:53] offset:128
	s_add_u32 s52, s52, 4096
	s_addc_u32 s53, s53, 0
	global_store_dword v122, v118, s[52:53]
	global_store_dword v122, v119, s[52:53] offset:128
	s_add_u32 s52, s52, 4096
	s_addc_u32 s53, s53, 0
	global_store_dword v122, v120, s[52:53]
	global_store_dword v122, v121, s[52:53] offset:128
	s_add_u32 s52, s52, 20480
	s_addc_u32 s53, s53, 0
	global_store_dword v122, v134, s[52:53]
	global_store_dword v122, v135, s[52:53] offset:128
	s_add_u32 s52, s52, 4096
	s_addc_u32 s53, s53, 0
	global_store_dword v122, v136, s[52:53]
	global_store_dword v122, v137, s[52:53] offset:128
	s_add_u32 s52, s52, 4096
	s_addc_u32 s53, s53, 0
	global_store_dword v122, v138, s[52:53]
	global_store_dword v122, v139, s[52:53] offset:128
	s_add_u32 s52, s52, 4096
	s_addc_u32 s53, s53, 0
	global_store_dword v122, v140, s[52:53]
	global_store_dword v122, v141, s[52:53] offset:128
	s_add_u32 s52, s80, 196608
	s_addc_u32 s53, s81, 0
	global_load_dword v114, v122, s[52:53]
	global_load_dword v115, v122, s[52:53] offset:128
	s_add_u32 s52, s52, 4096
	s_addc_u32 s53, s53, 0
	global_load_dword v116, v122, s[52:53]
	global_load_dword v117, v122, s[52:53] offset:128
	s_add_u32 s52, s52, 4096
	s_addc_u32 s53, s53, 0
	global_load_dword v118, v122, s[52:53]
	global_load_dword v119, v122, s[52:53] offset:128
	s_add_u32 s52, s52, 4096
	s_addc_u32 s53, s53, 0
	global_load_dword v120, v122, s[52:53]
	global_load_dword v121, v122, s[52:53] offset:128
	s_add_u32 s52, s52, 20480
	s_addc_u32 s53, s53, 0
	global_load_dword v134, v122, s[52:53]
	global_load_dword v135, v122, s[52:53] offset:128
	s_add_u32 s52, s52, 4096
	s_addc_u32 s53, s53, 0
	global_load_dword v136, v122, s[52:53]
	global_load_dword v137, v122, s[52:53] offset:128
	s_add_u32 s52, s52, 4096
	s_addc_u32 s53, s53, 0
	global_load_dword v138, v122, s[52:53]
	global_load_dword v139, v122, s[52:53] offset:128
	s_add_u32 s52, s52, 4096
	s_addc_u32 s53, s53, 0
	global_load_dword v140, v122, s[52:53]
	global_load_dword v141, v122, s[52:53] offset:128
	s_waitcnt vmcnt(0)
; template <int AI, int BI>
; DI void dn_tile(const Params& p, char* wsb, int layer, int sub, bool final_out, int m0, int n0, char* lds) {
;     ...
; #pragma unroll
;   for (int bi = 0; bi < BI; ++bi) {
;     const int n = n0 + wb * 32 * BI + bi * 32 + r;
;     const float gv = 0.5f * gate[n];
;     const unsigned ib = (unsigned)((m0e + wa * 32 * AI + 4 * h) * 1024 + n);
; #pragma unroll
;     for (int ai = 0; ai < AI; ++ai)
; #pragma unroll
;       for (int reg = 0; reg < 16; ++reg) {
;         const unsigned idx = ib + (unsigned)((ai * 32 + (reg & 3) + 8 * (reg >> 2)) * 1024);
;         float v = xsu[idx] + gv * acc[ai][bi][reg];
;         if (final_out) outu[idx] = v; else xsu[idx] = v;
;         if ((reg & 7) == 7) __builtin_amdgcn_sched_barrier(0);
;       }
;   }
	v_fmac_f32_e32 v114, v42, v124
	v_fmac_f32_e32 v115, v58, v142
	v_fmac_f32_e32 v116, v43, v124
	v_fmac_f32_e32 v117, v59, v142
	v_fmac_f32_e32 v118, v44, v124
	v_fmac_f32_e32 v119, v60, v142
	v_fmac_f32_e32 v120, v45, v124
	v_fmac_f32_e32 v121, v61, v142
	v_fmac_f32_e32 v134, v46, v124
	v_fmac_f32_e32 v135, v62, v142
	v_fmac_f32_e32 v136, v47, v124
	v_fmac_f32_e32 v137, v63, v142
	v_fmac_f32_e32 v138, v48, v124
	v_fmac_f32_e32 v139, v64, v142
	v_fmac_f32_e32 v140, v49, v124
	v_fmac_f32_e32 v141, v65, v142
	s_add_u32 s52, s82, 196608
	s_addc_u32 s53, s83, 0
	global_store_dword v122, v114, s[52:53]
	global_store_dword v122, v115, s[52:53] offset:128
	s_add_u32 s52, s52, 4096
	s_addc_u32 s53, s53, 0
	global_store_dword v122, v116, s[52:53]
	global_store_dword v122, v117, s[52:53] offset:128
	s_add_u32 s52, s52, 4096
	s_addc_u32 s53, s53, 0
	global_store_dword v122, v118, s[52:53]
	global_store_dword v122, v119, s[52:53] offset:128
	s_add_u32 s52, s52, 4096
	s_addc_u32 s53, s53, 0
	global_store_dword v122, v120, s[52:53]
	global_store_dword v122, v121, s[52:53] offset:128
	s_add_u32 s52, s52, 20480
	s_addc_u32 s53, s53, 0
	global_store_dword v122, v134, s[52:53]
	global_store_dword v122, v135, s[52:53] offset:128
	s_add_u32 s52, s52, 4096
	s_addc_u32 s53, s53, 0
	global_store_dword v122, v136, s[52:53]
	global_store_dword v122, v137, s[52:53] offset:128
	s_add_u32 s52, s52, 4096
	s_addc_u32 s53, s53, 0
	global_store_dword v122, v138, s[52:53]
	global_store_dword v122, v139, s[52:53] offset:128
	s_add_u32 s52, s52, 4096
	s_addc_u32 s53, s53, 0
	global_store_dword v122, v140, s[52:53]
	global_store_dword v122, v141, s[52:53] offset:128
	s_add_u32 s80, s80, 0x80000
	s_addc_u32 s81, s81, 0
	s_add_u32 s82, s82, 0x80000
	s_addc_u32 s83, s83, 0
	s_add_u32 s52, s80, 0
	s_addc_u32 s53, s81, 0
	global_load_dword v114, v122, s[52:53]
	global_load_dword v115, v122, s[52:53] offset:128
	s_add_u32 s52, s52, 4096
	s_addc_u32 s53, s53, 0
	global_load_dword v116, v122, s[52:53]
	global_load_dword v117, v122, s[52:53] offset:128
	s_add_u32 s52, s52, 4096
	s_addc_u32 s53, s53, 0
	global_load_dword v118, v122, s[52:53]
	global_load_dword v119, v122, s[52:53] offset:128
	s_add_u32 s52, s52, 4096
	s_addc_u32 s53, s53, 0
	global_load_dword v120, v122, s[52:53]
	global_load_dword v121, v122, s[52:53] offset:128
	s_add_u32 s52, s52, 20480
	s_addc_u32 s53, s53, 0
	global_load_dword v134, v122, s[52:53]
	global_load_dword v135, v122, s[52:53] offset:128
	s_add_u32 s52, s52, 4096
	s_addc_u32 s53, s53, 0
	global_load_dword v136, v122, s[52:53]
	global_load_dword v137, v122, s[52:53] offset:128
	s_add_u32 s52, s52, 4096
	s_addc_u32 s53, s53, 0
	global_load_dword v138, v122, s[52:53]
	global_load_dword v139, v122, s[52:53] offset:128
	s_add_u32 s52, s52, 4096
	s_addc_u32 s53, s53, 0
	global_load_dword v140, v122, s[52:53]
	global_load_dword v141, v122, s[52:53] offset:128
	s_waitcnt vmcnt(0)
	v_fmac_f32_e32 v114, v66, v124
	v_fmac_f32_e32 v115, v82, v142
	v_fmac_f32_e32 v116, v67, v124
	v_fmac_f32_e32 v117, v83, v142
	v_fmac_f32_e32 v118, v68, v124
	v_fmac_f32_e32 v119, v84, v142
	v_fmac_f32_e32 v120, v69, v124
	v_fmac_f32_e32 v121, v85, v142
	v_fmac_f32_e32 v134, v70, v124
	v_fmac_f32_e32 v135, v86, v142
	v_fmac_f32_e32 v136, v71, v124
	v_fmac_f32_e32 v137, v87, v142
	v_fmac_f32_e32 v138, v72, v124
	v_fmac_f32_e32 v139, v88, v142
	v_fmac_f32_e32 v140, v73, v124
	v_fmac_f32_e32 v141, v89, v142
	s_add_u32 s52, s82, 0
	s_addc_u32 s53, s83, 0
	global_store_dword v122, v114, s[52:53]
	global_store_dword v122, v115, s[52:53] offset:128
	s_add_u32 s52, s52, 4096
	s_addc_u32 s53, s53, 0
	global_store_dword v122, v116, s[52:53]
	global_store_dword v122, v117, s[52:53] offset:128
	s_add_u32 s52, s52, 4096
	s_addc_u32 s53, s53, 0
	global_store_dword v122, v118, s[52:53]
	global_store_dword v122, v119, s[52:53] offset:128
	s_add_u32 s52, s52, 4096
	s_addc_u32 s53, s53, 0
	global_store_dword v122, v120, s[52:53]
	global_store_dword v122, v121, s[52:53] offset:128
	s_add_u32 s52, s52, 20480
	s_addc_u32 s53, s53, 0
	global_store_dword v122, v134, s[52:53]
	global_store_dword v122, v135, s[52:53] offset:128
	s_add_u32 s52, s52, 4096
	s_addc_u32 s53, s53, 0
	global_store_dword v122, v136, s[52:53]
	global_store_dword v122, v137, s[52:53] offset:128
	s_add_u32 s52, s52, 4096
	s_addc_u32 s53, s53, 0
	global_store_dword v122, v138, s[52:53]
	global_store_dword v122, v139, s[52:53] offset:128
	s_add_u32 s52, s52, 4096
	s_addc_u32 s53, s53, 0
	global_store_dword v122, v140, s[52:53]
	global_store_dword v122, v141, s[52:53] offset:128
	s_add_u32 s52, s80, 65536
	s_addc_u32 s53, s81, 0
	global_load_dword v114, v122, s[52:53]
	global_load_dword v115, v122, s[52:53] offset:128
	s_add_u32 s52, s52, 4096
	s_addc_u32 s53, s53, 0
	global_load_dword v116, v122, s[52:53]
	global_load_dword v117, v122, s[52:53] offset:128
	s_add_u32 s52, s52, 4096
	s_addc_u32 s53, s53, 0
	global_load_dword v118, v122, s[52:53]
	global_load_dword v119, v122, s[52:53] offset:128
	s_add_u32 s52, s52, 4096
	s_addc_u32 s53, s53, 0
	global_load_dword v120, v122, s[52:53]
	global_load_dword v121, v122, s[52:53] offset:128
	s_add_u32 s52, s52, 20480
	s_addc_u32 s53, s53, 0
	global_load_dword v134, v122, s[52:53]
	global_load_dword v135, v122, s[52:53] offset:128
	s_add_u32 s52, s52, 4096
	s_addc_u32 s53, s53, 0
	global_load_dword v136, v122, s[52:53]
	global_load_dword v137, v122, s[52:53] offset:128
	s_add_u32 s52, s52, 4096
	s_addc_u32 s53, s53, 0
	global_load_dword v138, v122, s[52:53]
	global_load_dword v139, v122, s[52:53] offset:128
	s_add_u32 s52, s52, 4096
	s_addc_u32 s53, s53, 0
	global_load_dword v140, v122, s[52:53]
	global_load_dword v141, v122, s[52:53] offset:128
	s_waitcnt vmcnt(0)
; template <int AI, int BI>
; DI void dn_tile(const Params& p, char* wsb, int layer, int sub, bool final_out, int m0, int n0, char* lds) {
;     ...
; #pragma unroll
;   for (int bi = 0; bi < BI; ++bi) {
;     const int n = n0 + wb * 32 * BI + bi * 32 + r;
;     const float gv = 0.5f * gate[n];
;     const unsigned ib = (unsigned)((m0e + wa * 32 * AI + 4 * h) * 1024 + n);
; #pragma unroll
;     for (int ai = 0; ai < AI; ++ai)
; #pragma unroll
;       for (int reg = 0; reg < 16; ++reg) {
;         const unsigned idx = ib + (unsigned)((ai * 32 + (reg & 3) + 8 * (reg >> 2)) * 1024);
;         float v = xsu[idx] + gv * acc[ai][bi][reg];
;         if (final_out) outu[idx] = v; else xsu[idx] = v;
;         if ((reg & 7) == 7) __builtin_amdgcn_sched_barrier(0);
;       }
;   }
	v_fmac_f32_e32 v114, v74, v124
	v_fmac_f32_e32 v115, v90, v142
	v_fmac_f32_e32 v116, v75, v124
	v_fmac_f32_e32 v117, v91, v142
	v_fmac_f32_e32 v118, v76, v124
	v_fmac_f32_e32 v119, v92, v142
	v_fmac_f32_e32 v120, v77, v124
	v_fmac_f32_e32 v121, v93, v142
	v_fmac_f32_e32 v134, v78, v124
	v_fmac_f32_e32 v135, v94, v142
	v_fmac_f32_e32 v136, v79, v124
	v_fmac_f32_e32 v137, v95, v142
	v_fmac_f32_e32 v138, v80, v124
	v_fmac_f32_e32 v139, v96, v142
	v_fmac_f32_e32 v140, v81, v124
	v_fmac_f32_e32 v141, v97, v142
	s_add_u32 s52, s82, 65536
	s_addc_u32 s53, s83, 0
	global_store_dword v122, v114, s[52:53]
	global_store_dword v122, v115, s[52:53] offset:128
	s_add_u32 s52, s52, 4096
	s_addc_u32 s53, s53, 0
	global_store_dword v122, v116, s[52:53]
	global_store_dword v122, v117, s[52:53] offset:128
	s_add_u32 s52, s52, 4096
	s_addc_u32 s53, s53, 0
	global_store_dword v122, v118, s[52:53]
	global_store_dword v122, v119, s[52:53] offset:128
	s_add_u32 s52, s52, 4096
	s_addc_u32 s53, s53, 0
	global_store_dword v122, v120, s[52:53]
	global_store_dword v122, v121, s[52:53] offset:128
	s_add_u32 s52, s52, 20480
	s_addc_u32 s53, s53, 0
	global_store_dword v122, v134, s[52:53]
	global_store_dword v122, v135, s[52:53] offset:128
	s_add_u32 s52, s52, 4096
	s_addc_u32 s53, s53, 0
	global_store_dword v122, v136, s[52:53]
	global_store_dword v122, v137, s[52:53] offset:128
	s_add_u32 s52, s52, 4096
	s_addc_u32 s53, s53, 0
	global_store_dword v122, v138, s[52:53]
	global_store_dword v122, v139, s[52:53] offset:128
	s_add_u32 s52, s52, 4096
	s_addc_u32 s53, s53, 0
	global_store_dword v122, v140, s[52:53]
	global_store_dword v122, v141, s[52:53] offset:128
	s_add_u32 s52, s80, 131072
	s_addc_u32 s53, s81, 0
	global_load_dword v114, v122, s[52:53]
	global_load_dword v115, v122, s[52:53] offset:128
	s_add_u32 s52, s52, 4096
	s_addc_u32 s53, s53, 0
	global_load_dword v116, v122, s[52:53]
	global_load_dword v117, v122, s[52:53] offset:128
	s_add_u32 s52, s52, 4096
	s_addc_u32 s53, s53, 0
	global_load_dword v118, v122, s[52:53]
	global_load_dword v119, v122, s[52:53] offset:128
	s_add_u32 s52, s52, 4096
	s_addc_u32 s53, s53, 0
	global_load_dword v120, v122, s[52:53]
	global_load_dword v121, v122, s[52:53] offset:128
	s_add_u32 s52, s52, 20480
	s_addc_u32 s53, s53, 0
	global_load_dword v134, v122, s[52:53]
	global_load_dword v135, v122, s[52:53] offset:128
	s_add_u32 s52, s52, 4096
	s_addc_u32 s53, s53, 0
	global_load_dword v136, v122, s[52:53]
	global_load_dword v137, v122, s[52:53] offset:128
	s_add_u32 s52, s52, 4096
	s_addc_u32 s53, s53, 0
	global_load_dword v138, v122, s[52:53]
	global_load_dword v139, v122, s[52:53] offset:128
	s_add_u32 s52, s52, 4096
	s_addc_u32 s53, s53, 0
	global_load_dword v140, v122, s[52:53]
	global_load_dword v141, v122, s[52:53] offset:128
	s_waitcnt vmcnt(0)
; template <int AI, int BI>
; DI void dn_tile(const Params& p, char* wsb, int layer, int sub, bool final_out, int m0, int n0, char* lds) {
;     ...
; #pragma unroll
;   for (int bi = 0; bi < BI; ++bi) {
;     const int n = n0 + wb * 32 * BI + bi * 32 + r;
;     const float gv = 0.5f * gate[n];
;     const unsigned ib = (unsigned)((m0e + wa * 32 * AI + 4 * h) * 1024 + n);
; #pragma unroll
;     for (int ai = 0; ai < AI; ++ai)
; #pragma unroll
;       for (int reg = 0; reg < 16; ++reg) {
;         const unsigned idx = ib + (unsigned)((ai * 32 + (reg & 3) + 8 * (reg >> 2)) * 1024);
;         float v = xsu[idx] + gv * acc[ai][bi][reg];
;         if (final_out) outu[idx] = v; else xsu[idx] = v;
;         if ((reg & 7) == 7) __builtin_amdgcn_sched_barrier(0);
;       }
;   }
	v_fmac_f32_e32 v114, v98, v124
	v_fmac_f32_e32 v115, v214, v142
	v_fmac_f32_e32 v116, v99, v124
	v_fmac_f32_e32 v117, v215, v142
	v_fmac_f32_e32 v118, v100, v124
	v_fmac_f32_e32 v119, v216, v142
	v_fmac_f32_e32 v120, v101, v124
	v_fmac_f32_e32 v121, v217, v142
	v_fmac_f32_e32 v134, v102, v124
	v_fmac_f32_e32 v135, v218, v142
	v_fmac_f32_e32 v136, v103, v124
	v_fmac_f32_e32 v137, v219, v142
	v_fmac_f32_e32 v138, v104, v124
	v_fmac_f32_e32 v139, v220, v142
	v_fmac_f32_e32 v140, v105, v124
	v_fmac_f32_e32 v141, v221, v142
	s_add_u32 s52, s82, 131072
	s_addc_u32 s53, s83, 0
	global_store_dword v122, v114, s[52:53]
	global_store_dword v122, v115, s[52:53] offset:128
	s_add_u32 s52, s52, 4096
	s_addc_u32 s53, s53, 0
	global_store_dword v122, v116, s[52:53]
	global_store_dword v122, v117, s[52:53] offset:128
	s_add_u32 s52, s52, 4096
	s_addc_u32 s53, s53, 0
	global_store_dword v122, v118, s[52:53]
	global_store_dword v122, v119, s[52:53] offset:128
	s_add_u32 s52, s52, 4096
	s_addc_u32 s53, s53, 0
	global_store_dword v122, v120, s[52:53]
	global_store_dword v122, v121, s[52:53] offset:128
	s_add_u32 s52, s52, 20480
	s_addc_u32 s53, s53, 0
	global_store_dword v122, v134, s[52:53]
	global_store_dword v122, v135, s[52:53] offset:128
	s_add_u32 s52, s52, 4096
	s_addc_u32 s53, s53, 0
	global_store_dword v122, v136, s[52:53]
	global_store_dword v122, v137, s[52:53] offset:128
	s_add_u32 s52, s52, 4096
	s_addc_u32 s53, s53, 0
	global_store_dword v122, v138, s[52:53]
	global_store_dword v122, v139, s[52:53] offset:128
	s_add_u32 s52, s52, 4096
	s_addc_u32 s53, s53, 0
	global_store_dword v122, v140, s[52:53]
	global_store_dword v122, v141, s[52:53] offset:128
	s_add_u32 s52, s80, 196608
	s_addc_u32 s53, s81, 0
	global_load_dword v114, v122, s[52:53]
	global_load_dword v115, v122, s[52:53] offset:128
	s_add_u32 s52, s52, 4096
	s_addc_u32 s53, s53, 0
	global_load_dword v116, v122, s[52:53]
	global_load_dword v117, v122, s[52:53] offset:128
	s_add_u32 s52, s52, 4096
	s_addc_u32 s53, s53, 0
	global_load_dword v118, v122, s[52:53]
	global_load_dword v119, v122, s[52:53] offset:128
	s_add_u32 s52, s52, 4096
	s_addc_u32 s53, s53, 0
	global_load_dword v120, v122, s[52:53]
	global_load_dword v121, v122, s[52:53] offset:128
	s_add_u32 s52, s52, 20480
	s_addc_u32 s53, s53, 0
	global_load_dword v134, v122, s[52:53]
	global_load_dword v135, v122, s[52:53] offset:128
	s_add_u32 s52, s52, 4096
	s_addc_u32 s53, s53, 0
	global_load_dword v136, v122, s[52:53]
	global_load_dword v137, v122, s[52:53] offset:128
	s_add_u32 s52, s52, 4096
	s_addc_u32 s53, s53, 0
	global_load_dword v138, v122, s[52:53]
	global_load_dword v139, v122, s[52:53] offset:128
	s_add_u32 s52, s52, 4096
	s_addc_u32 s53, s53, 0
	global_load_dword v140, v122, s[52:53]
	global_load_dword v141, v122, s[52:53] offset:128
	s_waitcnt vmcnt(0)
	v_fmac_f32_e32 v114, v106, v124
	v_fmac_f32_e32 v115, v222, v142
	v_fmac_f32_e32 v116, v107, v124
	v_fmac_f32_e32 v117, v223, v142
	v_fmac_f32_e32 v118, v108, v124
	v_fmac_f32_e32 v119, v224, v142
	v_fmac_f32_e32 v120, v109, v124
	v_fmac_f32_e32 v121, v225, v142
	v_fmac_f32_e32 v134, v110, v124
	v_fmac_f32_e32 v135, v226, v142
	v_fmac_f32_e32 v136, v111, v124
	v_fmac_f32_e32 v137, v227, v142
	v_fmac_f32_e32 v138, v112, v124
	v_fmac_f32_e32 v139, v228, v142
	v_fmac_f32_e32 v140, v113, v124
	v_fmac_f32_e32 v141, v229, v142
	s_add_u32 s52, s82, 196608
	s_addc_u32 s53, s83, 0
	global_store_dword v122, v114, s[52:53]
	global_store_dword v122, v115, s[52:53] offset:128
	s_add_u32 s52, s52, 4096
	s_addc_u32 s53, s53, 0
	global_store_dword v122, v116, s[52:53]
	global_store_dword v122, v117, s[52:53] offset:128
	s_add_u32 s52, s52, 4096
	s_addc_u32 s53, s53, 0
	global_store_dword v122, v118, s[52:53]
	global_store_dword v122, v119, s[52:53] offset:128
	s_add_u32 s52, s52, 4096
	s_addc_u32 s53, s53, 0
	global_store_dword v122, v120, s[52:53]
	global_store_dword v122, v121, s[52:53] offset:128
	s_add_u32 s52, s52, 20480
	s_addc_u32 s53, s53, 0
	global_store_dword v122, v134, s[52:53]
	global_store_dword v122, v135, s[52:53] offset:128
	s_add_u32 s52, s52, 4096
	s_addc_u32 s53, s53, 0
	global_store_dword v122, v136, s[52:53]
	global_store_dword v122, v137, s[52:53] offset:128
	s_add_u32 s52, s52, 4096
	s_addc_u32 s53, s53, 0
	global_store_dword v122, v138, s[52:53]
	global_store_dword v122, v139, s[52:53] offset:128
	s_add_u32 s52, s52, 4096
	s_addc_u32 s53, s53, 0
	global_store_dword v122, v140, s[52:53]
	global_store_dword v122, v141, s[52:53] offset:128
	v_readlane_b32 s14, v243, 7
	s_mov_b32 s15, 0
	s_branch .LBB0_1521
